# MLA: waves 4-7 issue the next tile loads behind their 3rd PV MFMA; waves 0-3 read the first K fragments before issuing their tile loads
# speedup vs baseline: 1.0215x; 1.0122x over previous
; __device__ __forceinline__ void finishSM9(f32x16& p0, f32x16& p1, float alpha, float& l_reg, v8i32& p8) {
; #pragma unroll
;   for (int r = 0; r < 16; ++r) { p0[r] = __builtin_amdgcn_exp2f(p0[r]); p1[r] = __builtin_amdgcn_exp2f(p1[r]); }
;   float ps = 0;
; #pragma unroll
;   for (int r = 0; r < 16; ++r) ps += p0[r];
; #pragma unroll
;   for (int r = 0; r < 16; ++r) ps += p1[r];
;   { auto rr = __builtin_amdgcn_permlane32_swap(__float_as_uint(ps), __float_as_uint(ps), false, false);
;     ps = __uint_as_float(rr[0]) + __uint_as_float(rr[1]); }
;   l_reg = l_reg * alpha + ps;
; #pragma unroll
;   for (int g = 0; g < 4; ++g) {
;     int w = __builtin_amdgcn_cvt_pk_fp8_f32(p0[4 * g], p0[4 * g + 1], 0, false); p8[g] = __builtin_amdgcn_cvt_pk_fp8_f32(p0[4 * g + 2], p0[4 * g + 3], w, true);
;     int u = __builtin_amdgcn_cvt_pk_fp8_f32(p1[4 * g], p1[4 * g + 1], 0, false); p8[4 + g] = __builtin_amdgcn_cvt_pk_fp8_f32(p1[4 * g + 2], p1[4 * g + 3], u, true); }
; }
; __device__ __forceinline__ void pv8(f32x16* o, const char* Vt, const v8i32 p8, int r32, int hi) {
;   const int sw = (r32 >> 2) & 3, a0 = r32 * 64 + (((hi * 2) ^ sw) << 4), a1 = r32 * 64 + (((hi * 2 + 1) ^ sw) << 4);
; #pragma unroll
;   for (int d0 = 0; d0 < 4; ++d0) {
;     const v8i32 vf = cat8(*reinterpret_cast<const v4i32*>(Vt + d0 * 2048 + a0), *reinterpret_cast<const v4i32*>(Vt + d0 * 2048 + a1));
;     o[d0] = __builtin_amdgcn_mfma_scale_f32_32x32x64_f8f6f4(p8, vf, o[d0], 0, 0, 0, 127, 0, 127); }
; }
; __device__ __forceinline__ void qkt9(f32x16& p0, f32x16& p1, const char* Kn, const char* Kr, const v8i32* qf, const float init, int r32, int hi) {
; #pragma unroll
;   for (int r = 0; r < 16; ++r) { p0[r] = init; p1[r] = init; }
; #pragma unroll
;   for (int s = 0; s < 2; ++s) { const int c0 = s * 4 + hi * 2;
;     const v8i32 a0 = cat8(*reinterpret_cast<const v4i32*>(Kn + KN8SW(r32, c0)), *reinterpret_cast<const v4i32*>(Kn + KN8SW(r32, c0 + 1)));
;     const v8i32 a1 = cat8(*reinterpret_cast<const v4i32*>(Kn + 4096 + KN8SW(r32, c0)), *reinterpret_cast<const v4i32*>(Kn + 4096 + KN8SW(r32, c0 + 1)));
;     p0 = __builtin_amdgcn_mfma_scale_f32_32x32x64_f8f6f4(a0, qf[s], p0, 0, 0, 0, 127, 0, 124);
;     p1 = __builtin_amdgcn_mfma_scale_f32_32x32x64_f8f6f4(a1, qf[s], p1, 0, 0, 0, 127, 0, 124); }
;   { const int c0 = hi * 2;
.LBB0_1321:
	ds_read_b128 v[114:117], v215 offset:24576
	ds_read_b128 v[118:121], v216 offset:24576
	ds_read_b128 v[222:225], v215 offset:28672
	ds_read_b128 v[226:229], v216 offset:28672
	global_load_dwordx4 v[158:161], v176, s[18:19]
	global_load_dwordx4 v[162:165], v178, s[16:17]
	global_load_dwordx4 v[154:157], v[180:181], off
	v_add_u32_e32 v176, 0x2000, v176
	v_add_u32_e32 v178, 0x20000, v178
	s_mov_b64 s[20:21], 0x1000
	v_lshl_add_u64 v[180:181], v[180:181], 0, s[20:21]
	v_exp_f32_e32 v0, v82
	v_exp_f32_e32 v177, v83
	v_exp_f32_e32 v179, v84
	v_exp_f32_e32 v254, v85
	v_add_f32_e32 v219, v0, v177
	v_cvt_pk_fp8_f32 v246, v0, v177
	v_add_f32_e32 v219, v179, v219
	v_add_f32_e32 v219, v254, v219
	v_cvt_pk_fp8_f32 v246, v179, v254 op_sel:[0,0,1]
	s_waitcnt lgkmcnt(2)
	v_mfma_scale_f32_32x32x64_f8f6f4 v[114:129], v[114:121], v[146:153], v[230:245], v194, v193 op_sel_hi:[0,0,0]
	v_exp_f32_e32 v0, v86
	v_exp_f32_e32 v177, v87
	v_exp_f32_e32 v179, v88
	v_exp_f32_e32 v254, v89
	v_add_f32_e32 v219, v0, v219
	v_add_f32_e32 v219, v177, v219
	v_cvt_pk_fp8_f32 v247, v0, v177
	v_add_f32_e32 v219, v179, v219
	v_add_f32_e32 v219, v254, v219
	v_cvt_pk_fp8_f32 v247, v179, v254 op_sel:[0,0,1]
	ds_read_b128 v[82:85], v213 offset:24576
	ds_read_b128 v[86:89], v214 offset:24576
	s_waitcnt lgkmcnt(2)
	v_mfma_scale_f32_32x32x64_f8f6f4 v[98:113], v[222:229], v[146:153], v[230:245], v194, v193 op_sel_hi:[0,0,0]
	ds_read_b128 v[222:225], v213 offset:28672
	ds_read_b128 v[226:229], v214 offset:28672
	v_exp_f32_e32 v0, v90
	v_exp_f32_e32 v177, v91
	v_exp_f32_e32 v179, v92
	v_exp_f32_e32 v254, v93
	v_add_f32_e32 v219, v0, v219
	v_add_f32_e32 v219, v177, v219
	v_cvt_pk_fp8_f32 v248, v0, v177
	v_add_f32_e32 v219, v179, v219
	v_add_f32_e32 v219, v254, v219
	v_cvt_pk_fp8_f32 v248, v179, v254 op_sel:[0,0,1]
	v_exp_f32_e32 v0, v94
	v_exp_f32_e32 v177, v95
	v_exp_f32_e32 v179, v96
	v_exp_f32_e32 v254, v97
	v_add_f32_e32 v219, v0, v219
	v_add_f32_e32 v219, v177, v219
	v_cvt_pk_fp8_f32 v249, v0, v177
	v_add_f32_e32 v219, v179, v219
	v_add_f32_e32 v219, v254, v219
	v_cvt_pk_fp8_f32 v249, v179, v254 op_sel:[0,0,1]
	ds_read_b128 v[90:93], v185 offset:36864
	ds_read_b128 v[94:97], v186 offset:36864
	s_waitcnt lgkmcnt(4)
	v_mfma_scale_f32_32x32x64_f8f6f4 v[114:129], v[82:89], v[138:145], v[114:129], v194, v193 op_sel_hi:[0,0,0]
	v_exp_f32_e32 v0, v66
	v_exp_f32_e32 v177, v67
	v_exp_f32_e32 v179, v68
	v_exp_f32_e32 v254, v69
	v_add_f32_e32 v219, v0, v219
	v_add_f32_e32 v219, v177, v219
	v_cvt_pk_fp8_f32 v250, v0, v177
	v_add_f32_e32 v219, v179, v219
	v_add_f32_e32 v219, v254, v219
	v_cvt_pk_fp8_f32 v250, v179, v254 op_sel:[0,0,1]
	s_waitcnt lgkmcnt(2)
	v_mfma_scale_f32_32x32x64_f8f6f4 v[98:113], v[222:229], v[138:145], v[98:113], v194, v193 op_sel_hi:[0,0,0]
	ds_read_b128 v[222:225], v185 offset:38912
	ds_read_b128 v[226:229], v186 offset:38912
	v_exp_f32_e32 v0, v70
	v_exp_f32_e32 v177, v71
	v_exp_f32_e32 v179, v72
	v_exp_f32_e32 v254, v73
	v_add_f32_e32 v219, v0, v219
	v_add_f32_e32 v219, v177, v219
	v_cvt_pk_fp8_f32 v251, v0, v177
	v_add_f32_e32 v219, v179, v219
	v_add_f32_e32 v219, v254, v219
	v_cvt_pk_fp8_f32 v251, v179, v254 op_sel:[0,0,1]
	v_exp_f32_e32 v0, v74
	v_exp_f32_e32 v177, v75
	v_exp_f32_e32 v179, v76
	v_exp_f32_e32 v254, v77
	v_add_f32_e32 v219, v0, v219
	v_add_f32_e32 v219, v177, v219
	v_cvt_pk_fp8_f32 v252, v0, v177
	v_add_f32_e32 v219, v179, v219
	v_add_f32_e32 v219, v254, v219
	v_cvt_pk_fp8_f32 v252, v179, v254 op_sel:[0,0,1]
	s_waitcnt lgkmcnt(2)
	v_mfma_scale_f32_32x32x64_f8f6f4 v[114:129], v[90:97], v[130:137], v[114:129], v194, v193 op_sel_hi:[0,0,0]
	v_exp_f32_e32 v0, v78
	v_exp_f32_e32 v177, v79
	v_exp_f32_e32 v179, v80
	v_exp_f32_e32 v254, v81
	v_add_f32_e32 v219, v0, v219
	v_add_f32_e32 v219, v177, v219
	v_cvt_pk_fp8_f32 v253, v0, v177
	v_add_f32_e32 v219, v179, v219
	v_add_f32_e32 v219, v254, v219
	v_cvt_pk_fp8_f32 v253, v179, v254 op_sel:[0,0,1]
	ds_read_b128 v[90:93], v185 offset:0
	ds_read_b128 v[94:97], v186 offset:0
	ds_read_b128 v[82:85], v185 offset:2048
	ds_read_b128 v[86:89], v186 offset:2048
	ds_read_b128 v[74:77], v185 offset:4096
	ds_read_b128 v[78:81], v186 offset:4096
	ds_read_b128 v[66:69], v185 offset:6144
	ds_read_b128 v[70:73], v186 offset:6144
	s_waitcnt lgkmcnt(8)
	v_mfma_scale_f32_32x32x64_f8f6f4 v[98:113], v[222:229], v[130:137], v[98:113], v194, v193 op_sel_hi:[0,0,0]
	v_mov_b32_e32 v0, v219
	s_nop 1
	v_permlane32_swap_b32_e32 v219, v0
	v_add_f32_e32 v219, v219, v0
	v_fma_f32 v209, v209, v218, v219
	v_max_f32_e32 v177, v114, v115
	v_max3_f32 v177, v177, v116, v117
	v_max3_f32 v177, v177, v118, v119
	v_max3_f32 v177, v177, v120, v121
	v_max3_f32 v177, v177, v122, v123
	v_max3_f32 v177, v177, v124, v125
	v_max3_f32 v177, v177, v126, v127
	v_max3_f32 v177, v177, v128, v129
	s_waitcnt lgkmcnt(6)
	v_mfma_scale_f32_32x32x64_f8f6f4 v[50:65], v[246:253], v[90:97], v[50:65], v194, v194 op_sel_hi:[0,0,0]
	s_waitcnt lgkmcnt(4)
	v_mfma_scale_f32_32x32x64_f8f6f4 v[34:49], v[246:253], v[82:89], v[34:49], v194, v194 op_sel_hi:[0,0,0]
	s_waitcnt lgkmcnt(2)
	v_mfma_scale_f32_32x32x64_f8f6f4 v[18:33], v[246:253], v[74:81], v[18:33], v194, v194 op_sel_hi:[0,0,0]
	s_waitcnt vmcnt(0)
	ds_write_b128 v210, v[158:161] offset:43008
	ds_write_b128 v211, v[162:165] offset:51200
	ds_write_b128 v212, v[154:157] offset:59392
	s_waitcnt lgkmcnt(3)
	v_mfma_scale_f32_32x32x64_f8f6f4 v[2:17], v[246:253], v[66:73], v[2:17], v194, v194 op_sel_hi:[0,0,0]
	s_waitcnt lgkmcnt(0)
	s_barrier
	v_max_f32_e32 v0, v98, v99
	v_max3_f32 v0, v0, v100, v101
	v_max3_f32 v0, v0, v102, v103
	v_max3_f32 v0, v0, v104, v105
	v_max3_f32 v0, v0, v106, v107
	v_max3_f32 v0, v0, v108, v109
	v_max3_f32 v0, v0, v110, v111
	v_max3_f32 v0, v0, v112, v113
	v_max_f32_e32 v177, v177, v0
	v_mov_b32_e32 v0, v177
	v_mov_b32_e32 v221, 1.0
	s_nop 0
	v_permlane32_swap_b32_e32 v177, v0
	v_max_f32_e32 v177, v177, v0
	v_cmp_ge_f32_e32 vcc, s90, v177
	s_cmp_eq_u64 vcc, exec
	s_cbranch_scc0 .Lmla_h0_newmax
; __device__ __forceinline__ void finishSM9(f32x16& p0, f32x16& p1, float alpha, float& l_reg, v8i32& p8) {
; #pragma unroll
;   for (int r = 0; r < 16; ++r) { p0[r] = __builtin_amdgcn_exp2f(p0[r]); p1[r] = __builtin_amdgcn_exp2f(p1[r]); }
;   float ps = 0;
; #pragma unroll
;   for (int r = 0; r < 16; ++r) ps += p0[r];
; #pragma unroll
;   for (int r = 0; r < 16; ++r) ps += p1[r];
;   { auto rr = __builtin_amdgcn_permlane32_swap(__float_as_uint(ps), __float_as_uint(ps), false, false);
;     ps = __uint_as_float(rr[0]) + __uint_as_float(rr[1]); }
;   l_reg = l_reg * alpha + ps;
; #pragma unroll
;   for (int g = 0; g < 4; ++g) {
;     int w = __builtin_amdgcn_cvt_pk_fp8_f32(p0[4 * g], p0[4 * g + 1], 0, false); p8[g] = __builtin_amdgcn_cvt_pk_fp8_f32(p0[4 * g + 2], p0[4 * g + 3], w, true);
;     int u = __builtin_amdgcn_cvt_pk_fp8_f32(p1[4 * g], p1[4 * g + 1], 0, false); p8[4 + g] = __builtin_amdgcn_cvt_pk_fp8_f32(p1[4 * g + 2], p1[4 * g + 3], u, true); }
; }
; __device__ __forceinline__ void pv8(f32x16* o, const char* Vt, const v8i32 p8, int r32, int hi) {
;   const int sw = (r32 >> 2) & 3, a0 = r32 * 64 + (((hi * 2) ^ sw) << 4), a1 = r32 * 64 + (((hi * 2 + 1) ^ sw) << 4);
; #pragma unroll
;   for (int d0 = 0; d0 < 4; ++d0) {
;     const v8i32 vf = cat8(*reinterpret_cast<const v4i32*>(Vt + d0 * 2048 + a0), *reinterpret_cast<const v4i32*>(Vt + d0 * 2048 + a1));
;     o[d0] = __builtin_amdgcn_mfma_scale_f32_32x32x64_f8f6f4(p8, vf, o[d0], 0, 0, 0, 127, 0, 127); }
; }
; __device__ __forceinline__ void qkt9(f32x16& p0, f32x16& p1, const char* Kn, const char* Kr, const v8i32* qf, const float init, int r32, int hi) {
; #pragma unroll
;   for (int r = 0; r < 16; ++r) { p0[r] = init; p1[r] = init; }
; #pragma unroll
;   for (int s = 0; s < 2; ++s) { const int c0 = s * 4 + hi * 2;
;     const v8i32 a0 = cat8(*reinterpret_cast<const v4i32*>(Kn + KN8SW(r32, c0)), *reinterpret_cast<const v4i32*>(Kn + KN8SW(r32, c0 + 1)));
;     const v8i32 a1 = cat8(*reinterpret_cast<const v4i32*>(Kn + 4096 + KN8SW(r32, c0)), *reinterpret_cast<const v4i32*>(Kn + 4096 + KN8SW(r32, c0 + 1)));
;     p0 = __builtin_amdgcn_mfma_scale_f32_32x32x64_f8f6f4(a0, qf[s], p0, 0, 0, 0, 127, 0, 124);
;     p1 = __builtin_amdgcn_mfma_scale_f32_32x32x64_f8f6f4(a1, qf[s], p1, 0, 0, 0, 127, 0, 124); }
;   { const int c0 = hi * 2;
.Lmla_h0_cont:
	ds_read_b128 v[82:85], v215 offset:51200
	ds_read_b128 v[86:89], v216 offset:51200
	ds_read_b128 v[222:225], v215 offset:55296
	ds_read_b128 v[226:229], v216 offset:55296
	global_load_dwordx4 v[158:161], v176, s[18:19]
	global_load_dwordx4 v[162:165], v178, s[16:17]
	global_load_dwordx4 v[154:157], v[180:181], off
	v_add_u32_e32 v176, 0x2000, v176
	v_add_u32_e32 v178, 0x20000, v178
	s_mov_b64 s[20:21], 0x1000
	v_lshl_add_u64 v[180:181], v[180:181], 0, s[20:21]
	v_exp_f32_e32 v0, v114
	v_exp_f32_e32 v177, v115
	v_exp_f32_e32 v179, v116
	v_exp_f32_e32 v254, v117
	v_add_f32_e32 v219, v0, v177
	v_cvt_pk_fp8_f32 v246, v0, v177
	v_add_f32_e32 v219, v179, v219
	v_add_f32_e32 v219, v254, v219
	v_cvt_pk_fp8_f32 v246, v179, v254 op_sel:[0,0,1]
	s_waitcnt lgkmcnt(2)
	v_mfma_scale_f32_32x32x64_f8f6f4 v[82:97], v[82:89], v[146:153], v[230:245], v194, v193 op_sel_hi:[0,0,0]
	v_exp_f32_e32 v0, v118
	v_exp_f32_e32 v177, v119
	v_exp_f32_e32 v179, v120
	v_exp_f32_e32 v254, v121
	v_add_f32_e32 v219, v0, v219
	v_add_f32_e32 v219, v177, v219
	v_cvt_pk_fp8_f32 v247, v0, v177
	v_add_f32_e32 v219, v179, v219
	v_add_f32_e32 v219, v254, v219
	v_cvt_pk_fp8_f32 v247, v179, v254 op_sel:[0,0,1]
	ds_read_b128 v[114:117], v213 offset:51200
	ds_read_b128 v[118:121], v214 offset:51200
	s_waitcnt lgkmcnt(2)
	v_mfma_scale_f32_32x32x64_f8f6f4 v[66:81], v[222:229], v[146:153], v[230:245], v194, v193 op_sel_hi:[0,0,0]
	ds_read_b128 v[222:225], v213 offset:55296
	ds_read_b128 v[226:229], v214 offset:55296
	v_exp_f32_e32 v0, v122
	v_exp_f32_e32 v177, v123
	v_exp_f32_e32 v179, v124
	v_exp_f32_e32 v254, v125
	v_add_f32_e32 v219, v0, v219
	v_add_f32_e32 v219, v177, v219
	v_cvt_pk_fp8_f32 v248, v0, v177
	v_add_f32_e32 v219, v179, v219
	v_add_f32_e32 v219, v254, v219
	v_cvt_pk_fp8_f32 v248, v179, v254 op_sel:[0,0,1]
	v_exp_f32_e32 v0, v126
	v_exp_f32_e32 v177, v127
	v_exp_f32_e32 v179, v128
	v_exp_f32_e32 v254, v129
	v_add_f32_e32 v219, v0, v219
	v_add_f32_e32 v219, v177, v219
	v_cvt_pk_fp8_f32 v249, v0, v177
	v_add_f32_e32 v219, v179, v219
	v_add_f32_e32 v219, v254, v219
	v_cvt_pk_fp8_f32 v249, v179, v254 op_sel:[0,0,1]
	ds_read_b128 v[122:125], v185 offset:59392
	ds_read_b128 v[126:129], v186 offset:59392
	s_waitcnt lgkmcnt(4)
	v_mfma_scale_f32_32x32x64_f8f6f4 v[82:97], v[114:121], v[138:145], v[82:97], v194, v193 op_sel_hi:[0,0,0]
	v_exp_f32_e32 v0, v98
	v_exp_f32_e32 v177, v99
	v_exp_f32_e32 v179, v100
	v_exp_f32_e32 v254, v101
	v_add_f32_e32 v219, v0, v219
	v_add_f32_e32 v219, v177, v219
	v_cvt_pk_fp8_f32 v250, v0, v177
	v_add_f32_e32 v219, v179, v219
	v_add_f32_e32 v219, v254, v219
	v_cvt_pk_fp8_f32 v250, v179, v254 op_sel:[0,0,1]
	s_waitcnt lgkmcnt(2)
	v_mfma_scale_f32_32x32x64_f8f6f4 v[66:81], v[222:229], v[138:145], v[66:81], v194, v193 op_sel_hi:[0,0,0]
	ds_read_b128 v[222:225], v185 offset:61440
	ds_read_b128 v[226:229], v186 offset:61440
	v_exp_f32_e32 v0, v102
	v_exp_f32_e32 v177, v103
	v_exp_f32_e32 v179, v104
	v_exp_f32_e32 v254, v105
	v_add_f32_e32 v219, v0, v219
	v_add_f32_e32 v219, v177, v219
	v_cvt_pk_fp8_f32 v251, v0, v177
	v_add_f32_e32 v219, v179, v219
	v_add_f32_e32 v219, v254, v219
	v_cvt_pk_fp8_f32 v251, v179, v254 op_sel:[0,0,1]
	v_exp_f32_e32 v0, v106
	v_exp_f32_e32 v177, v107
	v_exp_f32_e32 v179, v108
	v_exp_f32_e32 v254, v109
	v_add_f32_e32 v219, v0, v219
	v_add_f32_e32 v219, v177, v219
	v_cvt_pk_fp8_f32 v252, v0, v177
	v_add_f32_e32 v219, v179, v219
	v_add_f32_e32 v219, v254, v219
	v_cvt_pk_fp8_f32 v252, v179, v254 op_sel:[0,0,1]
	s_waitcnt lgkmcnt(2)
	v_mfma_scale_f32_32x32x64_f8f6f4 v[82:97], v[122:129], v[130:137], v[82:97], v194, v193 op_sel_hi:[0,0,0]
	v_exp_f32_e32 v0, v110
	v_exp_f32_e32 v177, v111
	v_exp_f32_e32 v179, v112
	v_exp_f32_e32 v254, v113
	v_add_f32_e32 v219, v0, v219
	v_add_f32_e32 v219, v177, v219
	v_cvt_pk_fp8_f32 v253, v0, v177
	v_add_f32_e32 v219, v179, v219
	v_add_f32_e32 v219, v254, v219
	v_cvt_pk_fp8_f32 v253, v179, v254 op_sel:[0,0,1]
	ds_read_b128 v[122:125], v185 offset:8192
	ds_read_b128 v[126:129], v186 offset:8192
	ds_read_b128 v[114:117], v185 offset:10240
	ds_read_b128 v[118:121], v186 offset:10240
	ds_read_b128 v[106:109], v185 offset:12288
	ds_read_b128 v[110:113], v186 offset:12288
	ds_read_b128 v[98:101], v185 offset:14336
	ds_read_b128 v[102:105], v186 offset:14336
	s_waitcnt lgkmcnt(8)
	v_mfma_scale_f32_32x32x64_f8f6f4 v[66:81], v[222:229], v[130:137], v[66:81], v194, v193 op_sel_hi:[0,0,0]
	v_mov_b32_e32 v0, v219
	s_nop 1
	v_permlane32_swap_b32_e32 v219, v0
	v_add_f32_e32 v219, v219, v0
	v_fma_f32 v209, v209, v221, v219
	v_max_f32_e32 v177, v82, v83
	v_max3_f32 v177, v177, v84, v85
	v_max3_f32 v177, v177, v86, v87
	v_max3_f32 v177, v177, v88, v89
	v_max3_f32 v177, v177, v90, v91
	v_max3_f32 v177, v177, v92, v93
	v_max3_f32 v177, v177, v94, v95
	v_max3_f32 v177, v177, v96, v97
	s_waitcnt lgkmcnt(6)
	v_mfma_scale_f32_32x32x64_f8f6f4 v[50:65], v[246:253], v[122:129], v[50:65], v194, v194 op_sel_hi:[0,0,0]
	s_waitcnt lgkmcnt(4)
	v_mfma_scale_f32_32x32x64_f8f6f4 v[34:49], v[246:253], v[114:121], v[34:49], v194, v194 op_sel_hi:[0,0,0]
	s_waitcnt lgkmcnt(2)
	v_mfma_scale_f32_32x32x64_f8f6f4 v[18:33], v[246:253], v[106:113], v[18:33], v194, v194 op_sel_hi:[0,0,0]
	s_waitcnt vmcnt(0)
	ds_write_b128 v210, v[158:161]
	ds_write_b128 v211, v[162:165] offset:16384
	ds_write_b128 v212, v[154:157] offset:32768
	s_waitcnt lgkmcnt(3)
	v_mfma_scale_f32_32x32x64_f8f6f4 v[2:17], v[246:253], v[98:105], v[2:17], v194, v194 op_sel_hi:[0,0,0]
	s_waitcnt lgkmcnt(0)
	s_barrier
	v_max_f32_e32 v0, v66, v67
	v_max3_f32 v0, v0, v68, v69
	v_max3_f32 v0, v0, v70, v71
	v_max3_f32 v0, v0, v72, v73
	v_max3_f32 v0, v0, v74, v75
	v_max3_f32 v0, v0, v76, v77
	v_max3_f32 v0, v0, v78, v79
	v_max3_f32 v0, v0, v80, v81
	v_max_f32_e32 v177, v177, v0
	v_mov_b32_e32 v0, v177
	v_mov_b32_e32 v218, 1.0
	s_nop 0
	v_permlane32_swap_b32_e32 v177, v0
	v_max_f32_e32 v177, v177, v0
	v_cmp_ge_f32_e32 vcc, s90, v177
	s_cmp_eq_u64 vcc, exec
	s_cbranch_scc0 .Lmla_h1_newmax
; __device__ __forceinline__ void finishSM9(f32x16& p0, f32x16& p1, float alpha, float& l_reg, v8i32& p8) {
; #pragma unroll
;   for (int r = 0; r < 16; ++r) { p0[r] = __builtin_amdgcn_exp2f(p0[r]); p1[r] = __builtin_amdgcn_exp2f(p1[r]); }
;   float ps = 0;
; #pragma unroll
;   for (int r = 0; r < 16; ++r) ps += p0[r];
; #pragma unroll
;   for (int r = 0; r < 16; ++r) ps += p1[r];
;   { auto rr = __builtin_amdgcn_permlane32_swap(__float_as_uint(ps), __float_as_uint(ps), false, false);
;     ps = __uint_as_float(rr[0]) + __uint_as_float(rr[1]); }
;   l_reg = l_reg * alpha + ps;
; #pragma unroll
;   for (int g = 0; g < 4; ++g) {
;     int w = __builtin_amdgcn_cvt_pk_fp8_f32(p0[4 * g], p0[4 * g + 1], 0, false); p8[g] = __builtin_amdgcn_cvt_pk_fp8_f32(p0[4 * g + 2], p0[4 * g + 3], w, true);
;     int u = __builtin_amdgcn_cvt_pk_fp8_f32(p1[4 * g], p1[4 * g + 1], 0, false); p8[4 + g] = __builtin_amdgcn_cvt_pk_fp8_f32(p1[4 * g + 2], p1[4 * g + 3], u, true); }
; }
; __device__ __forceinline__ void pv8(f32x16* o, const char* Vt, const v8i32 p8, int r32, int hi) {
;   const int sw = (r32 >> 2) & 3, a0 = r32 * 64 + (((hi * 2) ^ sw) << 4), a1 = r32 * 64 + (((hi * 2 + 1) ^ sw) << 4);
; #pragma unroll
;   for (int d0 = 0; d0 < 4; ++d0) {
;     const v8i32 vf = cat8(*reinterpret_cast<const v4i32*>(Vt + d0 * 2048 + a0), *reinterpret_cast<const v4i32*>(Vt + d0 * 2048 + a1));
;     o[d0] = __builtin_amdgcn_mfma_scale_f32_32x32x64_f8f6f4(p8, vf, o[d0], 0, 0, 0, 127, 0, 127); }
; }
; __device__ __forceinline__ void qkt9(f32x16& p0, f32x16& p1, const char* Kn, const char* Kr, const v8i32* qf, const float init, int r32, int hi) {
; #pragma unroll
;   for (int r = 0; r < 16; ++r) { p0[r] = init; p1[r] = init; }
; #pragma unroll
;   for (int s = 0; s < 2; ++s) { const int c0 = s * 4 + hi * 2;
;     const v8i32 a0 = cat8(*reinterpret_cast<const v4i32*>(Kn + KN8SW(r32, c0)), *reinterpret_cast<const v4i32*>(Kn + KN8SW(r32, c0 + 1)));
;     const v8i32 a1 = cat8(*reinterpret_cast<const v4i32*>(Kn + 4096 + KN8SW(r32, c0)), *reinterpret_cast<const v4i32*>(Kn + 4096 + KN8SW(r32, c0 + 1)));
;     p0 = __builtin_amdgcn_mfma_scale_f32_32x32x64_f8f6f4(a0, qf[s], p0, 0, 0, 0, 127, 0, 124);
;     p1 = __builtin_amdgcn_mfma_scale_f32_32x32x64_f8f6f4(a1, qf[s], p1, 0, 0, 0, 127, 0, 124); }
;   { const int c0 = hi * 2;
.Lmla_h1_cont:
	ds_read_b128 v[114:117], v215 offset:16384
	ds_read_b128 v[118:121], v216 offset:16384
	ds_read_b128 v[222:225], v215 offset:20480
	ds_read_b128 v[226:229], v216 offset:20480
	global_load_dwordx4 v[158:161], v176, s[18:19]
	global_load_dwordx4 v[162:165], v178, s[16:17]
	global_load_dwordx4 v[154:157], v[180:181], off
	v_add_u32_e32 v176, 0x2000, v176
	v_add_u32_e32 v178, 0x20000, v178
	s_mov_b64 s[20:21], 0x1000
	v_lshl_add_u64 v[180:181], v[180:181], 0, s[20:21]
	v_exp_f32_e32 v0, v82
	v_exp_f32_e32 v177, v83
	v_exp_f32_e32 v179, v84
	v_exp_f32_e32 v254, v85
	v_add_f32_e32 v219, v0, v177
	v_cvt_pk_fp8_f32 v246, v0, v177
	v_add_f32_e32 v219, v179, v219
	v_add_f32_e32 v219, v254, v219
	v_cvt_pk_fp8_f32 v246, v179, v254 op_sel:[0,0,1]
	s_waitcnt lgkmcnt(2)
	v_mfma_scale_f32_32x32x64_f8f6f4 v[114:129], v[114:121], v[146:153], v[230:245], v194, v193 op_sel_hi:[0,0,0]
	v_exp_f32_e32 v0, v86
	v_exp_f32_e32 v177, v87
	v_exp_f32_e32 v179, v88
	v_exp_f32_e32 v254, v89
	v_add_f32_e32 v219, v0, v219
	v_add_f32_e32 v219, v177, v219
	v_cvt_pk_fp8_f32 v247, v0, v177
	v_add_f32_e32 v219, v179, v219
	v_add_f32_e32 v219, v254, v219
	v_cvt_pk_fp8_f32 v247, v179, v254 op_sel:[0,0,1]
	ds_read_b128 v[82:85], v213 offset:16384
	ds_read_b128 v[86:89], v214 offset:16384
	s_waitcnt lgkmcnt(2)
	v_mfma_scale_f32_32x32x64_f8f6f4 v[98:113], v[222:229], v[146:153], v[230:245], v194, v193 op_sel_hi:[0,0,0]
	ds_read_b128 v[222:225], v213 offset:20480
	ds_read_b128 v[226:229], v214 offset:20480
	v_exp_f32_e32 v0, v90
	v_exp_f32_e32 v177, v91
	v_exp_f32_e32 v179, v92
	v_exp_f32_e32 v254, v93
	v_add_f32_e32 v219, v0, v219
	v_add_f32_e32 v219, v177, v219
	v_cvt_pk_fp8_f32 v248, v0, v177
	v_add_f32_e32 v219, v179, v219
	v_add_f32_e32 v219, v254, v219
	v_cvt_pk_fp8_f32 v248, v179, v254 op_sel:[0,0,1]
	v_exp_f32_e32 v0, v94
	v_exp_f32_e32 v177, v95
	v_exp_f32_e32 v179, v96
	v_exp_f32_e32 v254, v97
	v_add_f32_e32 v219, v0, v219
	v_add_f32_e32 v219, v177, v219
	v_cvt_pk_fp8_f32 v249, v0, v177
	v_add_f32_e32 v219, v179, v219
	v_add_f32_e32 v219, v254, v219
	v_cvt_pk_fp8_f32 v249, v179, v254 op_sel:[0,0,1]
	ds_read_b128 v[90:93], v185 offset:32768
	ds_read_b128 v[94:97], v186 offset:32768
	s_waitcnt lgkmcnt(4)
	v_mfma_scale_f32_32x32x64_f8f6f4 v[114:129], v[82:89], v[138:145], v[114:129], v194, v193 op_sel_hi:[0,0,0]
	v_exp_f32_e32 v0, v66
	v_exp_f32_e32 v177, v67
	v_exp_f32_e32 v179, v68
	v_exp_f32_e32 v254, v69
	v_add_f32_e32 v219, v0, v219
	v_add_f32_e32 v219, v177, v219
	v_cvt_pk_fp8_f32 v250, v0, v177
	v_add_f32_e32 v219, v179, v219
	v_add_f32_e32 v219, v254, v219
	v_cvt_pk_fp8_f32 v250, v179, v254 op_sel:[0,0,1]
	s_waitcnt lgkmcnt(2)
	v_mfma_scale_f32_32x32x64_f8f6f4 v[98:113], v[222:229], v[138:145], v[98:113], v194, v193 op_sel_hi:[0,0,0]
	ds_read_b128 v[222:225], v185 offset:34816
	ds_read_b128 v[226:229], v186 offset:34816
	v_exp_f32_e32 v0, v70
	v_exp_f32_e32 v177, v71
	v_exp_f32_e32 v179, v72
	v_exp_f32_e32 v254, v73
	v_add_f32_e32 v219, v0, v219
	v_add_f32_e32 v219, v177, v219
	v_cvt_pk_fp8_f32 v251, v0, v177
	v_add_f32_e32 v219, v179, v219
	v_add_f32_e32 v219, v254, v219
	v_cvt_pk_fp8_f32 v251, v179, v254 op_sel:[0,0,1]
	v_exp_f32_e32 v0, v74
	v_exp_f32_e32 v177, v75
	v_exp_f32_e32 v179, v76
	v_exp_f32_e32 v254, v77
	v_add_f32_e32 v219, v0, v219
	v_add_f32_e32 v219, v177, v219
	v_cvt_pk_fp8_f32 v252, v0, v177
	v_add_f32_e32 v219, v179, v219
	v_add_f32_e32 v219, v254, v219
	v_cvt_pk_fp8_f32 v252, v179, v254 op_sel:[0,0,1]
	s_waitcnt lgkmcnt(2)
	v_mfma_scale_f32_32x32x64_f8f6f4 v[114:129], v[90:97], v[130:137], v[114:129], v194, v193 op_sel_hi:[0,0,0]
	v_exp_f32_e32 v0, v78
	v_exp_f32_e32 v177, v79
	v_exp_f32_e32 v179, v80
	v_exp_f32_e32 v254, v81
	v_add_f32_e32 v219, v0, v219
	v_add_f32_e32 v219, v177, v219
	v_cvt_pk_fp8_f32 v253, v0, v177
	v_add_f32_e32 v219, v179, v219
	v_add_f32_e32 v219, v254, v219
	v_cvt_pk_fp8_f32 v253, v179, v254 op_sel:[0,0,1]
	ds_read_b128 v[90:93], v185 offset:43008
	ds_read_b128 v[94:97], v186 offset:43008
	ds_read_b128 v[82:85], v185 offset:45056
	ds_read_b128 v[86:89], v186 offset:45056
	ds_read_b128 v[74:77], v185 offset:47104
	ds_read_b128 v[78:81], v186 offset:47104
	ds_read_b128 v[66:69], v185 offset:49152
	ds_read_b128 v[70:73], v186 offset:49152
	s_waitcnt lgkmcnt(8)
	v_mfma_scale_f32_32x32x64_f8f6f4 v[98:113], v[222:229], v[130:137], v[98:113], v194, v193 op_sel_hi:[0,0,0]
	v_mov_b32_e32 v0, v219
	s_nop 1
	v_permlane32_swap_b32_e32 v219, v0
	v_add_f32_e32 v219, v219, v0
	v_fma_f32 v209, v209, v218, v219
	v_max_f32_e32 v177, v114, v115
	v_max3_f32 v177, v177, v116, v117
	v_max3_f32 v177, v177, v118, v119
	v_max3_f32 v177, v177, v120, v121
	v_max3_f32 v177, v177, v122, v123
	v_max3_f32 v177, v177, v124, v125
	v_max3_f32 v177, v177, v126, v127
	v_max3_f32 v177, v177, v128, v129
	s_waitcnt lgkmcnt(6)
	v_mfma_scale_f32_32x32x64_f8f6f4 v[50:65], v[246:253], v[90:97], v[50:65], v194, v194 op_sel_hi:[0,0,0]
	s_waitcnt lgkmcnt(4)
	v_mfma_scale_f32_32x32x64_f8f6f4 v[34:49], v[246:253], v[82:89], v[34:49], v194, v194 op_sel_hi:[0,0,0]
	s_waitcnt lgkmcnt(2)
	v_mfma_scale_f32_32x32x64_f8f6f4 v[18:33], v[246:253], v[74:81], v[18:33], v194, v194 op_sel_hi:[0,0,0]
	s_waitcnt vmcnt(0)
	ds_write_b128 v210, v[158:161] offset:8192
	ds_write_b128 v211, v[162:165] offset:24576
	ds_write_b128 v212, v[154:157] offset:36864
	s_waitcnt lgkmcnt(3)
	v_mfma_scale_f32_32x32x64_f8f6f4 v[2:17], v[246:253], v[66:73], v[2:17], v194, v194 op_sel_hi:[0,0,0]
	s_waitcnt lgkmcnt(0)
	s_barrier
	v_max_f32_e32 v0, v98, v99
	v_max3_f32 v0, v0, v100, v101
	v_max3_f32 v0, v0, v102, v103
	v_max3_f32 v0, v0, v104, v105
	v_max3_f32 v0, v0, v106, v107
	v_max3_f32 v0, v0, v108, v109
	v_max3_f32 v0, v0, v110, v111
	v_max3_f32 v0, v0, v112, v113
	v_max_f32_e32 v177, v177, v0
	v_mov_b32_e32 v0, v177
	v_mov_b32_e32 v221, 1.0
	s_nop 0
	v_permlane32_swap_b32_e32 v177, v0
	v_max_f32_e32 v177, v177, v0
	v_cmp_ge_f32_e32 vcc, s90, v177
	s_cmp_eq_u64 vcc, exec
	s_cbranch_scc0 .Lmla_h2_newmax
; __device__ __forceinline__ void finishSM9(f32x16& p0, f32x16& p1, float alpha, float& l_reg, v8i32& p8) {
; #pragma unroll
;   for (int r = 0; r < 16; ++r) { p0[r] = __builtin_amdgcn_exp2f(p0[r]); p1[r] = __builtin_amdgcn_exp2f(p1[r]); }
;   float ps = 0;
; #pragma unroll
;   for (int r = 0; r < 16; ++r) ps += p0[r];
; #pragma unroll
;   for (int r = 0; r < 16; ++r) ps += p1[r];
;   { auto rr = __builtin_amdgcn_permlane32_swap(__float_as_uint(ps), __float_as_uint(ps), false, false);
;     ps = __uint_as_float(rr[0]) + __uint_as_float(rr[1]); }
;   l_reg = l_reg * alpha + ps;
; #pragma unroll
;   for (int g = 0; g < 4; ++g) {
;     int w = __builtin_amdgcn_cvt_pk_fp8_f32(p0[4 * g], p0[4 * g + 1], 0, false); p8[g] = __builtin_amdgcn_cvt_pk_fp8_f32(p0[4 * g + 2], p0[4 * g + 3], w, true);
;     int u = __builtin_amdgcn_cvt_pk_fp8_f32(p1[4 * g], p1[4 * g + 1], 0, false); p8[4 + g] = __builtin_amdgcn_cvt_pk_fp8_f32(p1[4 * g + 2], p1[4 * g + 3], u, true); }
; }
; __device__ __forceinline__ void pv8(f32x16* o, const char* Vt, const v8i32 p8, int r32, int hi) {
;   const int sw = (r32 >> 2) & 3, a0 = r32 * 64 + (((hi * 2) ^ sw) << 4), a1 = r32 * 64 + (((hi * 2 + 1) ^ sw) << 4);
; #pragma unroll
;   for (int d0 = 0; d0 < 4; ++d0) {
;     const v8i32 vf = cat8(*reinterpret_cast<const v4i32*>(Vt + d0 * 2048 + a0), *reinterpret_cast<const v4i32*>(Vt + d0 * 2048 + a1));
;     o[d0] = __builtin_amdgcn_mfma_scale_f32_32x32x64_f8f6f4(p8, vf, o[d0], 0, 0, 0, 127, 0, 127); }
; }
; __device__ __forceinline__ void qkt9(f32x16& p0, f32x16& p1, const char* Kn, const char* Kr, const v8i32* qf, const float init, int r32, int hi) {
; #pragma unroll
;   for (int r = 0; r < 16; ++r) { p0[r] = init; p1[r] = init; }
; #pragma unroll
;   for (int s = 0; s < 2; ++s) { const int c0 = s * 4 + hi * 2;
;     const v8i32 a0 = cat8(*reinterpret_cast<const v4i32*>(Kn + KN8SW(r32, c0)), *reinterpret_cast<const v4i32*>(Kn + KN8SW(r32, c0 + 1)));
;     const v8i32 a1 = cat8(*reinterpret_cast<const v4i32*>(Kn + 4096 + KN8SW(r32, c0)), *reinterpret_cast<const v4i32*>(Kn + 4096 + KN8SW(r32, c0 + 1)));
;     p0 = __builtin_amdgcn_mfma_scale_f32_32x32x64_f8f6f4(a0, qf[s], p0, 0, 0, 0, 127, 0, 124);
;     p1 = __builtin_amdgcn_mfma_scale_f32_32x32x64_f8f6f4(a1, qf[s], p1, 0, 0, 0, 127, 0, 124); }
;   { const int c0 = hi * 2;
.Lmla_h2_cont:
	ds_read_b128 v[82:85], v215 offset:24576
	ds_read_b128 v[86:89], v216 offset:24576
	ds_read_b128 v[222:225], v215 offset:28672
	ds_read_b128 v[226:229], v216 offset:28672
	global_load_dwordx4 v[158:161], v176, s[18:19]
	global_load_dwordx4 v[162:165], v178, s[16:17]
	global_load_dwordx4 v[154:157], v[180:181], off
	v_add_u32_e32 v176, 0x2000, v176
	v_add_u32_e32 v178, 0x20000, v178
	s_mov_b64 s[20:21], 0x1000
	v_lshl_add_u64 v[180:181], v[180:181], 0, s[20:21]
	v_exp_f32_e32 v0, v114
	v_exp_f32_e32 v177, v115
	v_exp_f32_e32 v179, v116
	v_exp_f32_e32 v254, v117
	v_add_f32_e32 v219, v0, v177
	v_cvt_pk_fp8_f32 v246, v0, v177
	v_add_f32_e32 v219, v179, v219
	v_add_f32_e32 v219, v254, v219
	v_cvt_pk_fp8_f32 v246, v179, v254 op_sel:[0,0,1]
	s_waitcnt lgkmcnt(2)
	v_mfma_scale_f32_32x32x64_f8f6f4 v[82:97], v[82:89], v[146:153], v[230:245], v194, v193 op_sel_hi:[0,0,0]
	v_exp_f32_e32 v0, v118
	v_exp_f32_e32 v177, v119
	v_exp_f32_e32 v179, v120
	v_exp_f32_e32 v254, v121
	v_add_f32_e32 v219, v0, v219
	v_add_f32_e32 v219, v177, v219
	v_cvt_pk_fp8_f32 v247, v0, v177
	v_add_f32_e32 v219, v179, v219
	v_add_f32_e32 v219, v254, v219
	v_cvt_pk_fp8_f32 v247, v179, v254 op_sel:[0,0,1]
	ds_read_b128 v[114:117], v213 offset:24576
	ds_read_b128 v[118:121], v214 offset:24576
	s_waitcnt lgkmcnt(2)
	v_mfma_scale_f32_32x32x64_f8f6f4 v[66:81], v[222:229], v[146:153], v[230:245], v194, v193 op_sel_hi:[0,0,0]
	ds_read_b128 v[222:225], v213 offset:28672
	ds_read_b128 v[226:229], v214 offset:28672
	v_exp_f32_e32 v0, v122
	v_exp_f32_e32 v177, v123
	v_exp_f32_e32 v179, v124
	v_exp_f32_e32 v254, v125
	v_add_f32_e32 v219, v0, v219
	v_add_f32_e32 v219, v177, v219
	v_cvt_pk_fp8_f32 v248, v0, v177
	v_add_f32_e32 v219, v179, v219
	v_add_f32_e32 v219, v254, v219
	v_cvt_pk_fp8_f32 v248, v179, v254 op_sel:[0,0,1]
	v_exp_f32_e32 v0, v126
	v_exp_f32_e32 v177, v127
	v_exp_f32_e32 v179, v128
	v_exp_f32_e32 v254, v129
	v_add_f32_e32 v219, v0, v219
	v_add_f32_e32 v219, v177, v219
	v_cvt_pk_fp8_f32 v249, v0, v177
	v_add_f32_e32 v219, v179, v219
	v_add_f32_e32 v219, v254, v219
	v_cvt_pk_fp8_f32 v249, v179, v254 op_sel:[0,0,1]
	ds_read_b128 v[122:125], v185 offset:36864
	ds_read_b128 v[126:129], v186 offset:36864
	s_waitcnt lgkmcnt(4)
	v_mfma_scale_f32_32x32x64_f8f6f4 v[82:97], v[114:121], v[138:145], v[82:97], v194, v193 op_sel_hi:[0,0,0]
	v_exp_f32_e32 v0, v98
	v_exp_f32_e32 v177, v99
	v_exp_f32_e32 v179, v100
	v_exp_f32_e32 v254, v101
	v_add_f32_e32 v219, v0, v219
	v_add_f32_e32 v219, v177, v219
	v_cvt_pk_fp8_f32 v250, v0, v177
	v_add_f32_e32 v219, v179, v219
	v_add_f32_e32 v219, v254, v219
	v_cvt_pk_fp8_f32 v250, v179, v254 op_sel:[0,0,1]
	s_waitcnt lgkmcnt(2)
	v_mfma_scale_f32_32x32x64_f8f6f4 v[66:81], v[222:229], v[138:145], v[66:81], v194, v193 op_sel_hi:[0,0,0]
	ds_read_b128 v[222:225], v185 offset:38912
	ds_read_b128 v[226:229], v186 offset:38912
	v_exp_f32_e32 v0, v102
	v_exp_f32_e32 v177, v103
	v_exp_f32_e32 v179, v104
	v_exp_f32_e32 v254, v105
	v_add_f32_e32 v219, v0, v219
	v_add_f32_e32 v219, v177, v219
	v_cvt_pk_fp8_f32 v251, v0, v177
	v_add_f32_e32 v219, v179, v219
	v_add_f32_e32 v219, v254, v219
	v_cvt_pk_fp8_f32 v251, v179, v254 op_sel:[0,0,1]
	v_exp_f32_e32 v0, v106
	v_exp_f32_e32 v177, v107
	v_exp_f32_e32 v179, v108
	v_exp_f32_e32 v254, v109
	v_add_f32_e32 v219, v0, v219
	v_add_f32_e32 v219, v177, v219
	v_cvt_pk_fp8_f32 v252, v0, v177
	v_add_f32_e32 v219, v179, v219
	v_add_f32_e32 v219, v254, v219
	v_cvt_pk_fp8_f32 v252, v179, v254 op_sel:[0,0,1]
	s_waitcnt lgkmcnt(2)
	v_mfma_scale_f32_32x32x64_f8f6f4 v[82:97], v[122:129], v[130:137], v[82:97], v194, v193 op_sel_hi:[0,0,0]
	v_exp_f32_e32 v0, v110
	v_exp_f32_e32 v177, v111
	v_exp_f32_e32 v179, v112
	v_exp_f32_e32 v254, v113
	v_add_f32_e32 v219, v0, v219
	v_add_f32_e32 v219, v177, v219
	v_cvt_pk_fp8_f32 v253, v0, v177
	v_add_f32_e32 v219, v179, v219
	v_add_f32_e32 v219, v254, v219
	v_cvt_pk_fp8_f32 v253, v179, v254 op_sel:[0,0,1]
	ds_read_b128 v[122:125], v185 offset:0
	ds_read_b128 v[126:129], v186 offset:0
	ds_read_b128 v[114:117], v185 offset:2048
	ds_read_b128 v[118:121], v186 offset:2048
	ds_read_b128 v[106:109], v185 offset:4096
	ds_read_b128 v[110:113], v186 offset:4096
	ds_read_b128 v[98:101], v185 offset:6144
	ds_read_b128 v[102:105], v186 offset:6144
	s_waitcnt lgkmcnt(8)
	v_mfma_scale_f32_32x32x64_f8f6f4 v[66:81], v[222:229], v[130:137], v[66:81], v194, v193 op_sel_hi:[0,0,0]
	v_mov_b32_e32 v0, v219
	s_nop 1
	v_permlane32_swap_b32_e32 v219, v0
	v_add_f32_e32 v219, v219, v0
	v_fma_f32 v209, v209, v221, v219
	v_max_f32_e32 v177, v82, v83
	v_max3_f32 v177, v177, v84, v85
	v_max3_f32 v177, v177, v86, v87
	v_max3_f32 v177, v177, v88, v89
	v_max3_f32 v177, v177, v90, v91
	v_max3_f32 v177, v177, v92, v93
	v_max3_f32 v177, v177, v94, v95
	v_max3_f32 v177, v177, v96, v97
	s_waitcnt lgkmcnt(6)
	v_mfma_scale_f32_32x32x64_f8f6f4 v[50:65], v[246:253], v[122:129], v[50:65], v194, v194 op_sel_hi:[0,0,0]
	s_waitcnt lgkmcnt(4)
	v_mfma_scale_f32_32x32x64_f8f6f4 v[34:49], v[246:253], v[114:121], v[34:49], v194, v194 op_sel_hi:[0,0,0]
	s_waitcnt lgkmcnt(2)
	v_mfma_scale_f32_32x32x64_f8f6f4 v[18:33], v[246:253], v[106:113], v[18:33], v194, v194 op_sel_hi:[0,0,0]
	s_waitcnt vmcnt(0)
	ds_write_b128 v210, v[158:161] offset:43008
	ds_write_b128 v211, v[162:165] offset:51200
	ds_write_b128 v212, v[154:157] offset:59392
	s_waitcnt lgkmcnt(3)
	v_mfma_scale_f32_32x32x64_f8f6f4 v[2:17], v[246:253], v[98:105], v[2:17], v194, v194 op_sel_hi:[0,0,0]
	s_waitcnt lgkmcnt(0)
	s_barrier
	v_max_f32_e32 v0, v66, v67
	v_max3_f32 v0, v0, v68, v69
	v_max3_f32 v0, v0, v70, v71
	v_max3_f32 v0, v0, v72, v73
	v_max3_f32 v0, v0, v74, v75
	v_max3_f32 v0, v0, v76, v77
	v_max3_f32 v0, v0, v78, v79
	v_max3_f32 v0, v0, v80, v81
	v_max_f32_e32 v177, v177, v0
	v_mov_b32_e32 v0, v177
	v_mov_b32_e32 v218, 1.0
	s_nop 0
	v_permlane32_swap_b32_e32 v177, v0
	v_max_f32_e32 v177, v177, v0
	v_cmp_ge_f32_e32 vcc, s90, v177
	s_cmp_eq_u64 vcc, exec
	s_cbranch_scc0 .Lmla_h3_newmax
; __device__ __forceinline__ void finishSM9(f32x16& p0, f32x16& p1, float alpha, float& l_reg, v8i32& p8) {
; #pragma unroll
;   for (int r = 0; r < 16; ++r) { p0[r] = __builtin_amdgcn_exp2f(p0[r]); p1[r] = __builtin_amdgcn_exp2f(p1[r]); }
;   float ps = 0;
; #pragma unroll
;   for (int r = 0; r < 16; ++r) ps += p0[r];
; #pragma unroll
;   for (int r = 0; r < 16; ++r) ps += p1[r];
;   { auto rr = __builtin_amdgcn_permlane32_swap(__float_as_uint(ps), __float_as_uint(ps), false, false);
;     ps = __uint_as_float(rr[0]) + __uint_as_float(rr[1]); }
;   l_reg = l_reg * alpha + ps;
; #pragma unroll
;   for (int g = 0; g < 4; ++g) {
;     int w = __builtin_amdgcn_cvt_pk_fp8_f32(p0[4 * g], p0[4 * g + 1], 0, false); p8[g] = __builtin_amdgcn_cvt_pk_fp8_f32(p0[4 * g + 2], p0[4 * g + 3], w, true);
;     int u = __builtin_amdgcn_cvt_pk_fp8_f32(p1[4 * g], p1[4 * g + 1], 0, false); p8[4 + g] = __builtin_amdgcn_cvt_pk_fp8_f32(p1[4 * g + 2], p1[4 * g + 3], u, true); }
; }
; __device__ __forceinline__ void pv8(f32x16* o, const char* Vt, const v8i32 p8, int r32, int hi) {
;   const int sw = (r32 >> 2) & 3, a0 = r32 * 64 + (((hi * 2) ^ sw) << 4), a1 = r32 * 64 + (((hi * 2 + 1) ^ sw) << 4);
; #pragma unroll
;   for (int d0 = 0; d0 < 4; ++d0) {
;     const v8i32 vf = cat8(*reinterpret_cast<const v4i32*>(Vt + d0 * 2048 + a0), *reinterpret_cast<const v4i32*>(Vt + d0 * 2048 + a1));
;     o[d0] = __builtin_amdgcn_mfma_scale_f32_32x32x64_f8f6f4(p8, vf, o[d0], 0, 0, 0, 127, 0, 127); }
; }
; __device__ __forceinline__ void qkt9(f32x16& p0, f32x16& p1, const char* Kn, const char* Kr, const v8i32* qf, const float init, int r32, int hi) {
; #pragma unroll
;   for (int r = 0; r < 16; ++r) { p0[r] = init; p1[r] = init; }
; #pragma unroll
;   for (int s = 0; s < 2; ++s) { const int c0 = s * 4 + hi * 2;
;     const v8i32 a0 = cat8(*reinterpret_cast<const v4i32*>(Kn + KN8SW(r32, c0)), *reinterpret_cast<const v4i32*>(Kn + KN8SW(r32, c0 + 1)));
;     const v8i32 a1 = cat8(*reinterpret_cast<const v4i32*>(Kn + 4096 + KN8SW(r32, c0)), *reinterpret_cast<const v4i32*>(Kn + 4096 + KN8SW(r32, c0 + 1)));
;     p0 = __builtin_amdgcn_mfma_scale_f32_32x32x64_f8f6f4(a0, qf[s], p0, 0, 0, 0, 127, 0, 124);
;     p1 = __builtin_amdgcn_mfma_scale_f32_32x32x64_f8f6f4(a1, qf[s], p1, 0, 0, 0, 127, 0, 124); }
;   { const int c0 = hi * 2;
.Lmla_h3_cont:
	ds_read_b128 v[114:117], v215 offset:51200
	ds_read_b128 v[118:121], v216 offset:51200
	ds_read_b128 v[222:225], v215 offset:55296
	ds_read_b128 v[226:229], v216 offset:55296
	global_load_dwordx4 v[158:161], v176, s[18:19]
	global_load_dwordx4 v[162:165], v178, s[16:17]
	global_load_dwordx4 v[154:157], v[180:181], off
	v_add_u32_e32 v176, 0x2000, v176
	v_add_u32_e32 v178, 0x20000, v178
	s_mov_b64 s[20:21], 0x1000
	v_lshl_add_u64 v[180:181], v[180:181], 0, s[20:21]
	v_exp_f32_e32 v0, v82
	v_exp_f32_e32 v177, v83
	v_exp_f32_e32 v179, v84
	v_exp_f32_e32 v254, v85
	v_add_f32_e32 v219, v0, v177
	v_cvt_pk_fp8_f32 v246, v0, v177
	v_add_f32_e32 v219, v179, v219
	v_add_f32_e32 v219, v254, v219
	v_cvt_pk_fp8_f32 v246, v179, v254 op_sel:[0,0,1]
	s_waitcnt lgkmcnt(2)
	v_mfma_scale_f32_32x32x64_f8f6f4 v[114:129], v[114:121], v[146:153], v[230:245], v194, v193 op_sel_hi:[0,0,0]
	v_exp_f32_e32 v0, v86
	v_exp_f32_e32 v177, v87
	v_exp_f32_e32 v179, v88
	v_exp_f32_e32 v254, v89
	v_add_f32_e32 v219, v0, v219
	v_add_f32_e32 v219, v177, v219
	v_cvt_pk_fp8_f32 v247, v0, v177
	v_add_f32_e32 v219, v179, v219
	v_add_f32_e32 v219, v254, v219
	v_cvt_pk_fp8_f32 v247, v179, v254 op_sel:[0,0,1]
	ds_read_b128 v[82:85], v213 offset:51200
	ds_read_b128 v[86:89], v214 offset:51200
	s_waitcnt lgkmcnt(2)
	v_mfma_scale_f32_32x32x64_f8f6f4 v[98:113], v[222:229], v[146:153], v[230:245], v194, v193 op_sel_hi:[0,0,0]
	ds_read_b128 v[222:225], v213 offset:55296
	ds_read_b128 v[226:229], v214 offset:55296
	v_exp_f32_e32 v0, v90
	v_exp_f32_e32 v177, v91
	v_exp_f32_e32 v179, v92
	v_exp_f32_e32 v254, v93
	v_add_f32_e32 v219, v0, v219
	v_add_f32_e32 v219, v177, v219
	v_cvt_pk_fp8_f32 v248, v0, v177
	v_add_f32_e32 v219, v179, v219
	v_add_f32_e32 v219, v254, v219
	v_cvt_pk_fp8_f32 v248, v179, v254 op_sel:[0,0,1]
	v_exp_f32_e32 v0, v94
	v_exp_f32_e32 v177, v95
	v_exp_f32_e32 v179, v96
	v_exp_f32_e32 v254, v97
	v_add_f32_e32 v219, v0, v219
	v_add_f32_e32 v219, v177, v219
	v_cvt_pk_fp8_f32 v249, v0, v177
	v_add_f32_e32 v219, v179, v219
	v_add_f32_e32 v219, v254, v219
	v_cvt_pk_fp8_f32 v249, v179, v254 op_sel:[0,0,1]
	ds_read_b128 v[90:93], v185 offset:59392
	ds_read_b128 v[94:97], v186 offset:59392
	s_waitcnt lgkmcnt(4)
	v_mfma_scale_f32_32x32x64_f8f6f4 v[114:129], v[82:89], v[138:145], v[114:129], v194, v193 op_sel_hi:[0,0,0]
	v_exp_f32_e32 v0, v66
	v_exp_f32_e32 v177, v67
	v_exp_f32_e32 v179, v68
	v_exp_f32_e32 v254, v69
	v_add_f32_e32 v219, v0, v219
	v_add_f32_e32 v219, v177, v219
	v_cvt_pk_fp8_f32 v250, v0, v177
	v_add_f32_e32 v219, v179, v219
	v_add_f32_e32 v219, v254, v219
	v_cvt_pk_fp8_f32 v250, v179, v254 op_sel:[0,0,1]
	s_waitcnt lgkmcnt(2)
	v_mfma_scale_f32_32x32x64_f8f6f4 v[98:113], v[222:229], v[138:145], v[98:113], v194, v193 op_sel_hi:[0,0,0]
	ds_read_b128 v[222:225], v185 offset:61440
	ds_read_b128 v[226:229], v186 offset:61440
	v_exp_f32_e32 v0, v70
	v_exp_f32_e32 v177, v71
	v_exp_f32_e32 v179, v72
	v_exp_f32_e32 v254, v73
	v_add_f32_e32 v219, v0, v219
	v_add_f32_e32 v219, v177, v219
	v_cvt_pk_fp8_f32 v251, v0, v177
	v_add_f32_e32 v219, v179, v219
	v_add_f32_e32 v219, v254, v219
	v_cvt_pk_fp8_f32 v251, v179, v254 op_sel:[0,0,1]
	v_exp_f32_e32 v0, v74
	v_exp_f32_e32 v177, v75
	v_exp_f32_e32 v179, v76
	v_exp_f32_e32 v254, v77
	v_add_f32_e32 v219, v0, v219
	v_add_f32_e32 v219, v177, v219
	v_cvt_pk_fp8_f32 v252, v0, v177
	v_add_f32_e32 v219, v179, v219
	v_add_f32_e32 v219, v254, v219
	v_cvt_pk_fp8_f32 v252, v179, v254 op_sel:[0,0,1]
	s_waitcnt lgkmcnt(2)
	v_mfma_scale_f32_32x32x64_f8f6f4 v[114:129], v[90:97], v[130:137], v[114:129], v194, v193 op_sel_hi:[0,0,0]
	v_exp_f32_e32 v0, v78
	v_exp_f32_e32 v177, v79
	v_exp_f32_e32 v179, v80
	v_exp_f32_e32 v254, v81
	v_add_f32_e32 v219, v0, v219
	v_add_f32_e32 v219, v177, v219
	v_cvt_pk_fp8_f32 v253, v0, v177
	v_add_f32_e32 v219, v179, v219
	v_add_f32_e32 v219, v254, v219
	v_cvt_pk_fp8_f32 v253, v179, v254 op_sel:[0,0,1]
	ds_read_b128 v[90:93], v185 offset:8192
	ds_read_b128 v[94:97], v186 offset:8192
	ds_read_b128 v[82:85], v185 offset:10240
	ds_read_b128 v[86:89], v186 offset:10240
	ds_read_b128 v[74:77], v185 offset:12288
	ds_read_b128 v[78:81], v186 offset:12288
	ds_read_b128 v[66:69], v185 offset:14336
	ds_read_b128 v[70:73], v186 offset:14336
	s_waitcnt lgkmcnt(8)
	v_mfma_scale_f32_32x32x64_f8f6f4 v[98:113], v[222:229], v[130:137], v[98:113], v194, v193 op_sel_hi:[0,0,0]
	v_mov_b32_e32 v0, v219
	s_nop 1
	v_permlane32_swap_b32_e32 v219, v0
	v_add_f32_e32 v219, v219, v0
	v_fma_f32 v209, v209, v218, v219
	v_max_f32_e32 v177, v114, v115
	v_max3_f32 v177, v177, v116, v117
	v_max3_f32 v177, v177, v118, v119
	v_max3_f32 v177, v177, v120, v121
	v_max3_f32 v177, v177, v122, v123
	v_max3_f32 v177, v177, v124, v125
	v_max3_f32 v177, v177, v126, v127
	v_max3_f32 v177, v177, v128, v129
	s_waitcnt lgkmcnt(6)
	v_mfma_scale_f32_32x32x64_f8f6f4 v[50:65], v[246:253], v[90:97], v[50:65], v194, v194 op_sel_hi:[0,0,0]
	s_waitcnt lgkmcnt(4)
	v_mfma_scale_f32_32x32x64_f8f6f4 v[34:49], v[246:253], v[82:89], v[34:49], v194, v194 op_sel_hi:[0,0,0]
	s_waitcnt lgkmcnt(2)
	v_mfma_scale_f32_32x32x64_f8f6f4 v[18:33], v[246:253], v[74:81], v[18:33], v194, v194 op_sel_hi:[0,0,0]
	s_waitcnt vmcnt(0)
	ds_write_b128 v210, v[158:161]
	ds_write_b128 v211, v[162:165] offset:16384
	ds_write_b128 v212, v[154:157] offset:32768
	s_waitcnt lgkmcnt(3)
	v_mfma_scale_f32_32x32x64_f8f6f4 v[2:17], v[246:253], v[66:73], v[2:17], v194, v194 op_sel_hi:[0,0,0]
	s_waitcnt lgkmcnt(0)
	s_barrier
	v_max_f32_e32 v0, v98, v99
	v_max3_f32 v0, v0, v100, v101
	v_max3_f32 v0, v0, v102, v103
	v_max3_f32 v0, v0, v104, v105
	v_max3_f32 v0, v0, v106, v107
	v_max3_f32 v0, v0, v108, v109
	v_max3_f32 v0, v0, v110, v111
	v_max3_f32 v0, v0, v112, v113
	v_max_f32_e32 v177, v177, v0
	v_mov_b32_e32 v0, v177
	v_mov_b32_e32 v221, 1.0
	s_nop 0
	v_permlane32_swap_b32_e32 v177, v0
	v_max_f32_e32 v177, v177, v0
	v_cmp_ge_f32_e32 vcc, s90, v177
	s_cmp_eq_u64 vcc, exec
	s_cbranch_scc0 .Lmla_h4_newmax
; __device__ __forceinline__ void finishSM9(f32x16& p0, f32x16& p1, float alpha, float& l_reg, v8i32& p8) {
; #pragma unroll
;   for (int r = 0; r < 16; ++r) { p0[r] = __builtin_amdgcn_exp2f(p0[r]); p1[r] = __builtin_amdgcn_exp2f(p1[r]); }
;   float ps = 0;
; #pragma unroll
;   for (int r = 0; r < 16; ++r) ps += p0[r];
; #pragma unroll
;   for (int r = 0; r < 16; ++r) ps += p1[r];
;   { auto rr = __builtin_amdgcn_permlane32_swap(__float_as_uint(ps), __float_as_uint(ps), false, false);
;     ps = __uint_as_float(rr[0]) + __uint_as_float(rr[1]); }
;   l_reg = l_reg * alpha + ps;
; #pragma unroll
;   for (int g = 0; g < 4; ++g) {
;     int w = __builtin_amdgcn_cvt_pk_fp8_f32(p0[4 * g], p0[4 * g + 1], 0, false); p8[g] = __builtin_amdgcn_cvt_pk_fp8_f32(p0[4 * g + 2], p0[4 * g + 3], w, true);
;     int u = __builtin_amdgcn_cvt_pk_fp8_f32(p1[4 * g], p1[4 * g + 1], 0, false); p8[4 + g] = __builtin_amdgcn_cvt_pk_fp8_f32(p1[4 * g + 2], p1[4 * g + 3], u, true); }
; }
; __device__ __forceinline__ void pv8(f32x16* o, const char* Vt, const v8i32 p8, int r32, int hi) {
;   const int sw = (r32 >> 2) & 3, a0 = r32 * 64 + (((hi * 2) ^ sw) << 4), a1 = r32 * 64 + (((hi * 2 + 1) ^ sw) << 4);
; #pragma unroll
;   for (int d0 = 0; d0 < 4; ++d0) {
;     const v8i32 vf = cat8(*reinterpret_cast<const v4i32*>(Vt + d0 * 2048 + a0), *reinterpret_cast<const v4i32*>(Vt + d0 * 2048 + a1));
;     o[d0] = __builtin_amdgcn_mfma_scale_f32_32x32x64_f8f6f4(p8, vf, o[d0], 0, 0, 0, 127, 0, 127); }
; }
; __device__ __forceinline__ void qkt9(f32x16& p0, f32x16& p1, const char* Kn, const char* Kr, const v8i32* qf, const float init, int r32, int hi) {
; #pragma unroll
;   for (int r = 0; r < 16; ++r) { p0[r] = init; p1[r] = init; }
; #pragma unroll
;   for (int s = 0; s < 2; ++s) { const int c0 = s * 4 + hi * 2;
;     const v8i32 a0 = cat8(*reinterpret_cast<const v4i32*>(Kn + KN8SW(r32, c0)), *reinterpret_cast<const v4i32*>(Kn + KN8SW(r32, c0 + 1)));
;     const v8i32 a1 = cat8(*reinterpret_cast<const v4i32*>(Kn + 4096 + KN8SW(r32, c0)), *reinterpret_cast<const v4i32*>(Kn + 4096 + KN8SW(r32, c0 + 1)));
;     p0 = __builtin_amdgcn_mfma_scale_f32_32x32x64_f8f6f4(a0, qf[s], p0, 0, 0, 0, 127, 0, 124);
;     p1 = __builtin_amdgcn_mfma_scale_f32_32x32x64_f8f6f4(a1, qf[s], p1, 0, 0, 0, 127, 0, 124); }
;   { const int c0 = hi * 2;
.Lmla_h4_cont:
	ds_read_b128 v[82:85], v215 offset:16384
	ds_read_b128 v[86:89], v216 offset:16384
	ds_read_b128 v[222:225], v215 offset:20480
	ds_read_b128 v[226:229], v216 offset:20480
	global_load_dwordx4 v[158:161], v176, s[18:19]
	global_load_dwordx4 v[162:165], v178, s[16:17]
	global_load_dwordx4 v[154:157], v[180:181], off
	v_add_u32_e32 v176, 0x2000, v176
	v_add_u32_e32 v178, 0x20000, v178
	s_mov_b64 s[20:21], 0x1000
	v_lshl_add_u64 v[180:181], v[180:181], 0, s[20:21]
	v_exp_f32_e32 v0, v114
	v_exp_f32_e32 v177, v115
	v_exp_f32_e32 v179, v116
	v_exp_f32_e32 v254, v117
	v_add_f32_e32 v219, v0, v177
	v_cvt_pk_fp8_f32 v246, v0, v177
	v_add_f32_e32 v219, v179, v219
	v_add_f32_e32 v219, v254, v219
	v_cvt_pk_fp8_f32 v246, v179, v254 op_sel:[0,0,1]
	s_waitcnt lgkmcnt(2)
	v_mfma_scale_f32_32x32x64_f8f6f4 v[82:97], v[82:89], v[146:153], v[230:245], v194, v193 op_sel_hi:[0,0,0]
	v_exp_f32_e32 v0, v118
	v_exp_f32_e32 v177, v119
	v_exp_f32_e32 v179, v120
	v_exp_f32_e32 v254, v121
	v_add_f32_e32 v219, v0, v219
	v_add_f32_e32 v219, v177, v219
	v_cvt_pk_fp8_f32 v247, v0, v177
	v_add_f32_e32 v219, v179, v219
	v_add_f32_e32 v219, v254, v219
	v_cvt_pk_fp8_f32 v247, v179, v254 op_sel:[0,0,1]
	ds_read_b128 v[114:117], v213 offset:16384
	ds_read_b128 v[118:121], v214 offset:16384
	s_waitcnt lgkmcnt(2)
	v_mfma_scale_f32_32x32x64_f8f6f4 v[66:81], v[222:229], v[146:153], v[230:245], v194, v193 op_sel_hi:[0,0,0]
	ds_read_b128 v[222:225], v213 offset:20480
	ds_read_b128 v[226:229], v214 offset:20480
	v_exp_f32_e32 v0, v122
	v_exp_f32_e32 v177, v123
	v_exp_f32_e32 v179, v124
	v_exp_f32_e32 v254, v125
	v_add_f32_e32 v219, v0, v219
	v_add_f32_e32 v219, v177, v219
	v_cvt_pk_fp8_f32 v248, v0, v177
	v_add_f32_e32 v219, v179, v219
	v_add_f32_e32 v219, v254, v219
	v_cvt_pk_fp8_f32 v248, v179, v254 op_sel:[0,0,1]
	v_exp_f32_e32 v0, v126
	v_exp_f32_e32 v177, v127
	v_exp_f32_e32 v179, v128
	v_exp_f32_e32 v254, v129
	v_add_f32_e32 v219, v0, v219
	v_add_f32_e32 v219, v177, v219
	v_cvt_pk_fp8_f32 v249, v0, v177
	v_add_f32_e32 v219, v179, v219
	v_add_f32_e32 v219, v254, v219
	v_cvt_pk_fp8_f32 v249, v179, v254 op_sel:[0,0,1]
	ds_read_b128 v[122:125], v185 offset:32768
	ds_read_b128 v[126:129], v186 offset:32768
	s_waitcnt lgkmcnt(4)
	v_mfma_scale_f32_32x32x64_f8f6f4 v[82:97], v[114:121], v[138:145], v[82:97], v194, v193 op_sel_hi:[0,0,0]
	v_exp_f32_e32 v0, v98
	v_exp_f32_e32 v177, v99
	v_exp_f32_e32 v179, v100
	v_exp_f32_e32 v254, v101
	v_add_f32_e32 v219, v0, v219
	v_add_f32_e32 v219, v177, v219
	v_cvt_pk_fp8_f32 v250, v0, v177
	v_add_f32_e32 v219, v179, v219
	v_add_f32_e32 v219, v254, v219
	v_cvt_pk_fp8_f32 v250, v179, v254 op_sel:[0,0,1]
	s_waitcnt lgkmcnt(2)
	v_mfma_scale_f32_32x32x64_f8f6f4 v[66:81], v[222:229], v[138:145], v[66:81], v194, v193 op_sel_hi:[0,0,0]
	ds_read_b128 v[222:225], v185 offset:34816
	ds_read_b128 v[226:229], v186 offset:34816
	v_exp_f32_e32 v0, v102
	v_exp_f32_e32 v177, v103
	v_exp_f32_e32 v179, v104
	v_exp_f32_e32 v254, v105
	v_add_f32_e32 v219, v0, v219
	v_add_f32_e32 v219, v177, v219
	v_cvt_pk_fp8_f32 v251, v0, v177
	v_add_f32_e32 v219, v179, v219
	v_add_f32_e32 v219, v254, v219
	v_cvt_pk_fp8_f32 v251, v179, v254 op_sel:[0,0,1]
	v_exp_f32_e32 v0, v106
	v_exp_f32_e32 v177, v107
	v_exp_f32_e32 v179, v108
	v_exp_f32_e32 v254, v109
	v_add_f32_e32 v219, v0, v219
	v_add_f32_e32 v219, v177, v219
	v_cvt_pk_fp8_f32 v252, v0, v177
	v_add_f32_e32 v219, v179, v219
	v_add_f32_e32 v219, v254, v219
	v_cvt_pk_fp8_f32 v252, v179, v254 op_sel:[0,0,1]
	s_waitcnt lgkmcnt(2)
	v_mfma_scale_f32_32x32x64_f8f6f4 v[82:97], v[122:129], v[130:137], v[82:97], v194, v193 op_sel_hi:[0,0,0]
	v_exp_f32_e32 v0, v110
	v_exp_f32_e32 v177, v111
	v_exp_f32_e32 v179, v112
	v_exp_f32_e32 v254, v113
	v_add_f32_e32 v219, v0, v219
	v_add_f32_e32 v219, v177, v219
	v_cvt_pk_fp8_f32 v253, v0, v177
	v_add_f32_e32 v219, v179, v219
	v_add_f32_e32 v219, v254, v219
	v_cvt_pk_fp8_f32 v253, v179, v254 op_sel:[0,0,1]
	ds_read_b128 v[122:125], v185 offset:43008
	ds_read_b128 v[126:129], v186 offset:43008
	ds_read_b128 v[114:117], v185 offset:45056
	ds_read_b128 v[118:121], v186 offset:45056
	ds_read_b128 v[106:109], v185 offset:47104
	ds_read_b128 v[110:113], v186 offset:47104
	ds_read_b128 v[98:101], v185 offset:49152
	ds_read_b128 v[102:105], v186 offset:49152
	s_waitcnt lgkmcnt(8)
	v_mfma_scale_f32_32x32x64_f8f6f4 v[66:81], v[222:229], v[130:137], v[66:81], v194, v193 op_sel_hi:[0,0,0]
	v_mov_b32_e32 v0, v219
	s_nop 1
	v_permlane32_swap_b32_e32 v219, v0
	v_add_f32_e32 v219, v219, v0
	v_fma_f32 v209, v209, v221, v219
	v_max_f32_e32 v177, v82, v83
	v_max3_f32 v177, v177, v84, v85
	v_max3_f32 v177, v177, v86, v87
	v_max3_f32 v177, v177, v88, v89
	v_max3_f32 v177, v177, v90, v91
	v_max3_f32 v177, v177, v92, v93
	v_max3_f32 v177, v177, v94, v95
	v_max3_f32 v177, v177, v96, v97
	s_waitcnt lgkmcnt(6)
	v_mfma_scale_f32_32x32x64_f8f6f4 v[50:65], v[246:253], v[122:129], v[50:65], v194, v194 op_sel_hi:[0,0,0]
	s_waitcnt lgkmcnt(4)
	v_mfma_scale_f32_32x32x64_f8f6f4 v[34:49], v[246:253], v[114:121], v[34:49], v194, v194 op_sel_hi:[0,0,0]
	s_waitcnt lgkmcnt(2)
	v_mfma_scale_f32_32x32x64_f8f6f4 v[18:33], v[246:253], v[106:113], v[18:33], v194, v194 op_sel_hi:[0,0,0]
	s_waitcnt vmcnt(0)
	ds_write_b128 v210, v[158:161] offset:8192
	ds_write_b128 v211, v[162:165] offset:24576
	ds_write_b128 v212, v[154:157] offset:36864
	s_waitcnt lgkmcnt(3)
	v_mfma_scale_f32_32x32x64_f8f6f4 v[2:17], v[246:253], v[98:105], v[2:17], v194, v194 op_sel_hi:[0,0,0]
	s_waitcnt lgkmcnt(0)
	s_barrier
	v_max_f32_e32 v0, v66, v67
	v_max3_f32 v0, v0, v68, v69
	v_max3_f32 v0, v0, v70, v71
	v_max3_f32 v0, v0, v72, v73
	v_max3_f32 v0, v0, v74, v75
	v_max3_f32 v0, v0, v76, v77
	v_max3_f32 v0, v0, v78, v79
	v_max3_f32 v0, v0, v80, v81
	v_max_f32_e32 v177, v177, v0
	v_mov_b32_e32 v0, v177
	v_mov_b32_e32 v218, 1.0
	s_nop 0
	v_permlane32_swap_b32_e32 v177, v0
	v_max_f32_e32 v177, v177, v0
	v_cmp_ge_f32_e32 vcc, s90, v177
	s_cmp_eq_u64 vcc, exec
	s_cbranch_scc0 .Lmla_h5_newmax
; __device__ __forceinline__ void finishSM9(f32x16& p0, f32x16& p1, float alpha, float& l_reg, v8i32& p8) {
; #pragma unroll
;   for (int r = 0; r < 16; ++r) { p0[r] = __builtin_amdgcn_exp2f(p0[r]); p1[r] = __builtin_amdgcn_exp2f(p1[r]); }
;   float ps = 0;
; #pragma unroll
;   for (int r = 0; r < 16; ++r) ps += p0[r];
; #pragma unroll
;   for (int r = 0; r < 16; ++r) ps += p1[r];
;   { auto rr = __builtin_amdgcn_permlane32_swap(__float_as_uint(ps), __float_as_uint(ps), false, false);
;     ps = __uint_as_float(rr[0]) + __uint_as_float(rr[1]); }
;   l_reg = l_reg * alpha + ps;
; #pragma unroll
;   for (int g = 0; g < 4; ++g) {
;     int w = __builtin_amdgcn_cvt_pk_fp8_f32(p0[4 * g], p0[4 * g + 1], 0, false); p8[g] = __builtin_amdgcn_cvt_pk_fp8_f32(p0[4 * g + 2], p0[4 * g + 3], w, true);
;     int u = __builtin_amdgcn_cvt_pk_fp8_f32(p1[4 * g], p1[4 * g + 1], 0, false); p8[4 + g] = __builtin_amdgcn_cvt_pk_fp8_f32(p1[4 * g + 2], p1[4 * g + 3], u, true); }
; }
; __device__ __forceinline__ void pv8(f32x16* o, const char* Vt, const v8i32 p8, int r32, int hi) {
;   const int sw = (r32 >> 2) & 3, a0 = r32 * 64 + (((hi * 2) ^ sw) << 4), a1 = r32 * 64 + (((hi * 2 + 1) ^ sw) << 4);
; #pragma unroll
;   for (int d0 = 0; d0 < 4; ++d0) {
;     const v8i32 vf = cat8(*reinterpret_cast<const v4i32*>(Vt + d0 * 2048 + a0), *reinterpret_cast<const v4i32*>(Vt + d0 * 2048 + a1));
;     o[d0] = __builtin_amdgcn_mfma_scale_f32_32x32x64_f8f6f4(p8, vf, o[d0], 0, 0, 0, 127, 0, 127); }
; }
; __device__ __forceinline__ void qkt9(f32x16& p0, f32x16& p1, const char* Kn, const char* Kr, const v8i32* qf, const float init, int r32, int hi) {
; #pragma unroll
;   for (int r = 0; r < 16; ++r) { p0[r] = init; p1[r] = init; }
; #pragma unroll
;   for (int s = 0; s < 2; ++s) { const int c0 = s * 4 + hi * 2;
;     const v8i32 a0 = cat8(*reinterpret_cast<const v4i32*>(Kn + KN8SW(r32, c0)), *reinterpret_cast<const v4i32*>(Kn + KN8SW(r32, c0 + 1)));
;     const v8i32 a1 = cat8(*reinterpret_cast<const v4i32*>(Kn + 4096 + KN8SW(r32, c0)), *reinterpret_cast<const v4i32*>(Kn + 4096 + KN8SW(r32, c0 + 1)));
;     p0 = __builtin_amdgcn_mfma_scale_f32_32x32x64_f8f6f4(a0, qf[s], p0, 0, 0, 0, 127, 0, 124);
;     p1 = __builtin_amdgcn_mfma_scale_f32_32x32x64_f8f6f4(a1, qf[s], p1, 0, 0, 0, 127, 0, 124); }
;   { const int c0 = hi * 2;
.Lmla_h5_cont:
	s_add_i32 s30, s30, 1
	s_cmpk_lt_u32 s30, 42
	s_cbranch_scc1 .LBB0_1321
	ds_read_b128 v[114:117], v215 offset:24576
	ds_read_b128 v[118:121], v216 offset:24576
	ds_read_b128 v[222:225], v215 offset:28672
	ds_read_b128 v[226:229], v216 offset:28672
	global_load_dwordx4 v[158:161], v176, s[18:19]
	global_load_dwordx4 v[162:165], v178, s[16:17]
	global_load_dwordx4 v[154:157], v[180:181], off
	v_add_u32_e32 v176, 0x2000, v176
	v_add_u32_e32 v178, 0x20000, v178
	s_mov_b64 s[20:21], 0x1000
	v_lshl_add_u64 v[180:181], v[180:181], 0, s[20:21]
	v_exp_f32_e32 v0, v82
	v_exp_f32_e32 v177, v83
	v_exp_f32_e32 v179, v84
	v_exp_f32_e32 v254, v85
	v_add_f32_e32 v219, v0, v177
	v_cvt_pk_fp8_f32 v246, v0, v177
	v_add_f32_e32 v219, v179, v219
	v_add_f32_e32 v219, v254, v219
	v_cvt_pk_fp8_f32 v246, v179, v254 op_sel:[0,0,1]
	s_waitcnt lgkmcnt(2)
	v_mfma_scale_f32_32x32x64_f8f6f4 v[114:129], v[114:121], v[146:153], v[230:245], v194, v193 op_sel_hi:[0,0,0]
	v_exp_f32_e32 v0, v86
	v_exp_f32_e32 v177, v87
	v_exp_f32_e32 v179, v88
	v_exp_f32_e32 v254, v89
	v_add_f32_e32 v219, v0, v219
	v_add_f32_e32 v219, v177, v219
	v_cvt_pk_fp8_f32 v247, v0, v177
	v_add_f32_e32 v219, v179, v219
	v_add_f32_e32 v219, v254, v219
	v_cvt_pk_fp8_f32 v247, v179, v254 op_sel:[0,0,1]
	ds_read_b128 v[82:85], v213 offset:24576
	ds_read_b128 v[86:89], v214 offset:24576
	s_waitcnt lgkmcnt(2)
	v_mfma_scale_f32_32x32x64_f8f6f4 v[98:113], v[222:229], v[146:153], v[230:245], v194, v193 op_sel_hi:[0,0,0]
	ds_read_b128 v[222:225], v213 offset:28672
	ds_read_b128 v[226:229], v214 offset:28672
	v_exp_f32_e32 v0, v90
	v_exp_f32_e32 v177, v91
	v_exp_f32_e32 v179, v92
	v_exp_f32_e32 v254, v93
	v_add_f32_e32 v219, v0, v219
	v_add_f32_e32 v219, v177, v219
	v_cvt_pk_fp8_f32 v248, v0, v177
	v_add_f32_e32 v219, v179, v219
	v_add_f32_e32 v219, v254, v219
	v_cvt_pk_fp8_f32 v248, v179, v254 op_sel:[0,0,1]
	v_exp_f32_e32 v0, v94
	v_exp_f32_e32 v177, v95
	v_exp_f32_e32 v179, v96
	v_exp_f32_e32 v254, v97
	v_add_f32_e32 v219, v0, v219
	v_add_f32_e32 v219, v177, v219
	v_cvt_pk_fp8_f32 v249, v0, v177
	v_add_f32_e32 v219, v179, v219
	v_add_f32_e32 v219, v254, v219
	v_cvt_pk_fp8_f32 v249, v179, v254 op_sel:[0,0,1]
	ds_read_b128 v[90:93], v185 offset:36864
	ds_read_b128 v[94:97], v186 offset:36864
	s_waitcnt lgkmcnt(4)
	v_mfma_scale_f32_32x32x64_f8f6f4 v[114:129], v[82:89], v[138:145], v[114:129], v194, v193 op_sel_hi:[0,0,0]
	v_exp_f32_e32 v0, v66
	v_exp_f32_e32 v177, v67
	v_exp_f32_e32 v179, v68
	v_exp_f32_e32 v254, v69
	v_add_f32_e32 v219, v0, v219
	v_add_f32_e32 v219, v177, v219
	v_cvt_pk_fp8_f32 v250, v0, v177
	v_add_f32_e32 v219, v179, v219
	v_add_f32_e32 v219, v254, v219
	v_cvt_pk_fp8_f32 v250, v179, v254 op_sel:[0,0,1]
	s_waitcnt lgkmcnt(2)
	v_mfma_scale_f32_32x32x64_f8f6f4 v[98:113], v[222:229], v[138:145], v[98:113], v194, v193 op_sel_hi:[0,0,0]
	ds_read_b128 v[222:225], v185 offset:38912
	ds_read_b128 v[226:229], v186 offset:38912
	v_exp_f32_e32 v0, v70
	v_exp_f32_e32 v177, v71
	v_exp_f32_e32 v179, v72
	v_exp_f32_e32 v254, v73
	v_add_f32_e32 v219, v0, v219
	v_add_f32_e32 v219, v177, v219
	v_cvt_pk_fp8_f32 v251, v0, v177
	v_add_f32_e32 v219, v179, v219
	v_add_f32_e32 v219, v254, v219
	v_cvt_pk_fp8_f32 v251, v179, v254 op_sel:[0,0,1]
	v_exp_f32_e32 v0, v74
	v_exp_f32_e32 v177, v75
	v_exp_f32_e32 v179, v76
	v_exp_f32_e32 v254, v77
	v_add_f32_e32 v219, v0, v219
	v_add_f32_e32 v219, v177, v219
	v_cvt_pk_fp8_f32 v252, v0, v177
	v_add_f32_e32 v219, v179, v219
	v_add_f32_e32 v219, v254, v219
	v_cvt_pk_fp8_f32 v252, v179, v254 op_sel:[0,0,1]
	s_waitcnt lgkmcnt(2)
	v_mfma_scale_f32_32x32x64_f8f6f4 v[114:129], v[90:97], v[130:137], v[114:129], v194, v193 op_sel_hi:[0,0,0]
	v_exp_f32_e32 v0, v78
	v_exp_f32_e32 v177, v79
	v_exp_f32_e32 v179, v80
	v_exp_f32_e32 v254, v81
	v_add_f32_e32 v219, v0, v219
	v_add_f32_e32 v219, v177, v219
	v_cvt_pk_fp8_f32 v253, v0, v177
	v_add_f32_e32 v219, v179, v219
	v_add_f32_e32 v219, v254, v219
	v_cvt_pk_fp8_f32 v253, v179, v254 op_sel:[0,0,1]
	ds_read_b128 v[90:93], v185 offset:0
	ds_read_b128 v[94:97], v186 offset:0
	ds_read_b128 v[82:85], v185 offset:2048
	ds_read_b128 v[86:89], v186 offset:2048
	ds_read_b128 v[74:77], v185 offset:4096
	ds_read_b128 v[78:81], v186 offset:4096
	ds_read_b128 v[66:69], v185 offset:6144
	ds_read_b128 v[70:73], v186 offset:6144
	s_waitcnt lgkmcnt(8)
	v_mfma_scale_f32_32x32x64_f8f6f4 v[98:113], v[222:229], v[130:137], v[98:113], v194, v193 op_sel_hi:[0,0,0]
	v_mov_b32_e32 v0, v219
	s_nop 1
	v_permlane32_swap_b32_e32 v219, v0
	v_add_f32_e32 v219, v219, v0
	v_fma_f32 v209, v209, v218, v219
	v_max_f32_e32 v177, v114, v115
	v_max3_f32 v177, v177, v116, v117
	v_max3_f32 v177, v177, v118, v119
	v_max3_f32 v177, v177, v120, v121
	v_max3_f32 v177, v177, v122, v123
	v_max3_f32 v177, v177, v124, v125
	v_max3_f32 v177, v177, v126, v127
	v_max3_f32 v177, v177, v128, v129
	s_waitcnt lgkmcnt(6)
	v_mfma_scale_f32_32x32x64_f8f6f4 v[50:65], v[246:253], v[90:97], v[50:65], v194, v194 op_sel_hi:[0,0,0]
	s_waitcnt lgkmcnt(4)
	v_mfma_scale_f32_32x32x64_f8f6f4 v[34:49], v[246:253], v[82:89], v[34:49], v194, v194 op_sel_hi:[0,0,0]
	s_waitcnt lgkmcnt(2)
	v_mfma_scale_f32_32x32x64_f8f6f4 v[18:33], v[246:253], v[74:81], v[18:33], v194, v194 op_sel_hi:[0,0,0]
	s_waitcnt vmcnt(0)
	ds_write_b128 v210, v[158:161] offset:43008
	ds_write_b128 v211, v[162:165] offset:51200
	ds_write_b128 v212, v[154:157] offset:59392
	s_waitcnt lgkmcnt(3)
	v_mfma_scale_f32_32x32x64_f8f6f4 v[2:17], v[246:253], v[66:73], v[2:17], v194, v194 op_sel_hi:[0,0,0]
	s_waitcnt lgkmcnt(0)
	s_barrier
	v_max_f32_e32 v0, v98, v99
	v_max3_f32 v0, v0, v100, v101
	v_max3_f32 v0, v0, v102, v103
	v_max3_f32 v0, v0, v104, v105
	v_max3_f32 v0, v0, v106, v107
	v_max3_f32 v0, v0, v108, v109
	v_max3_f32 v0, v0, v110, v111
	v_max3_f32 v0, v0, v112, v113
	v_max_f32_e32 v177, v177, v0
	v_mov_b32_e32 v0, v177
	v_mov_b32_e32 v221, 1.0
	s_nop 0
	v_permlane32_swap_b32_e32 v177, v0
	v_max_f32_e32 v177, v177, v0
	v_cmp_ge_f32_e32 vcc, s90, v177
	s_cmp_eq_u64 vcc, exec
	s_cbranch_scc0 .Lmla_p0_newmax

; __device__ __forceinline__ void finishSM9(f32x16& p0, f32x16& p1, float alpha, float& l_reg, v8i32& p8) {
; #pragma unroll
;   for (int r = 0; r < 16; ++r) { p0[r] = __builtin_amdgcn_exp2f(p0[r]); p1[r] = __builtin_amdgcn_exp2f(p1[r]); }
;   float ps = 0;
; #pragma unroll
;   for (int r = 0; r < 16; ++r) ps += p0[r];
; #pragma unroll
;   for (int r = 0; r < 16; ++r) ps += p1[r];
;   { auto rr = __builtin_amdgcn_permlane32_swap(__float_as_uint(ps), __float_as_uint(ps), false, false);
;     ps = __uint_as_float(rr[0]) + __uint_as_float(rr[1]); }
;   l_reg = l_reg * alpha + ps;
; #pragma unroll
;   for (int g = 0; g < 4; ++g) {
;     int w = __builtin_amdgcn_cvt_pk_fp8_f32(p0[4 * g], p0[4 * g + 1], 0, false); p8[g] = __builtin_amdgcn_cvt_pk_fp8_f32(p0[4 * g + 2], p0[4 * g + 3], w, true);
;     int u = __builtin_amdgcn_cvt_pk_fp8_f32(p1[4 * g], p1[4 * g + 1], 0, false); p8[4 + g] = __builtin_amdgcn_cvt_pk_fp8_f32(p1[4 * g + 2], p1[4 * g + 3], u, true); }
; }
; __device__ __forceinline__ void pv8(f32x16* o, const char* Vt, const v8i32 p8, int r32, int hi) {
;   const int sw = (r32 >> 2) & 3, a0 = r32 * 64 + (((hi * 2) ^ sw) << 4), a1 = r32 * 64 + (((hi * 2 + 1) ^ sw) << 4);
; #pragma unroll
;   for (int d0 = 0; d0 < 4; ++d0) {
;     const v8i32 vf = cat8(*reinterpret_cast<const v4i32*>(Vt + d0 * 2048 + a0), *reinterpret_cast<const v4i32*>(Vt + d0 * 2048 + a1));
;     o[d0] = __builtin_amdgcn_mfma_scale_f32_32x32x64_f8f6f4(p8, vf, o[d0], 0, 0, 0, 127, 0, 127); }
; }
; __device__ __forceinline__ void qkt9(f32x16& p0, f32x16& p1, const char* Kn, const char* Kr, const v8i32* qf, const float init, int r32, int hi) {
; #pragma unroll
;   for (int r = 0; r < 16; ++r) { p0[r] = init; p1[r] = init; }
; #pragma unroll
;   for (int s = 0; s < 2; ++s) { const int c0 = s * 4 + hi * 2;
;     const v8i32 a0 = cat8(*reinterpret_cast<const v4i32*>(Kn + KN8SW(r32, c0)), *reinterpret_cast<const v4i32*>(Kn + KN8SW(r32, c0 + 1)));
;     const v8i32 a1 = cat8(*reinterpret_cast<const v4i32*>(Kn + 4096 + KN8SW(r32, c0)), *reinterpret_cast<const v4i32*>(Kn + 4096 + KN8SW(r32, c0 + 1)));
;     p0 = __builtin_amdgcn_mfma_scale_f32_32x32x64_f8f6f4(a0, qf[s], p0, 0, 0, 0, 127, 0, 124);
;     p1 = __builtin_amdgcn_mfma_scale_f32_32x32x64_f8f6f4(a1, qf[s], p1, 0, 0, 0, 127, 0, 124); }
;   { const int c0 = hi * 2;
.Lmla_stag_loop:
	ds_read_b128 v[114:117], v215 offset:24576
	ds_read_b128 v[118:121], v216 offset:24576
	ds_read_b128 v[222:225], v215 offset:28672
	ds_read_b128 v[226:229], v216 offset:28672
	v_exp_f32_e32 v0, v82
	v_exp_f32_e32 v177, v83
	v_exp_f32_e32 v179, v84
	v_exp_f32_e32 v254, v85
	v_add_f32_e32 v219, v0, v177
	v_cvt_pk_fp8_f32 v246, v0, v177
	v_add_f32_e32 v219, v179, v219
	v_add_f32_e32 v219, v254, v219
	v_cvt_pk_fp8_f32 v246, v179, v254 op_sel:[0,0,1]
	s_waitcnt lgkmcnt(2)
	v_mfma_scale_f32_32x32x64_f8f6f4 v[114:129], v[114:121], v[146:153], v[230:245], v194, v193 op_sel_hi:[0,0,0]
	v_exp_f32_e32 v0, v86
	v_exp_f32_e32 v177, v87
	v_exp_f32_e32 v179, v88
	v_exp_f32_e32 v254, v89
	v_add_f32_e32 v219, v0, v219
	v_add_f32_e32 v219, v177, v219
	v_cvt_pk_fp8_f32 v247, v0, v177
	v_add_f32_e32 v219, v179, v219
	v_add_f32_e32 v219, v254, v219
	v_cvt_pk_fp8_f32 v247, v179, v254 op_sel:[0,0,1]
	ds_read_b128 v[82:85], v213 offset:24576
	ds_read_b128 v[86:89], v214 offset:24576
	s_waitcnt lgkmcnt(2)
	v_mfma_scale_f32_32x32x64_f8f6f4 v[98:113], v[222:229], v[146:153], v[230:245], v194, v193 op_sel_hi:[0,0,0]
	ds_read_b128 v[222:225], v213 offset:28672
	ds_read_b128 v[226:229], v214 offset:28672
	v_exp_f32_e32 v0, v90
	v_exp_f32_e32 v177, v91
	v_exp_f32_e32 v179, v92
	v_exp_f32_e32 v254, v93
	v_add_f32_e32 v219, v0, v219
	v_add_f32_e32 v219, v177, v219
	v_cvt_pk_fp8_f32 v248, v0, v177
	v_add_f32_e32 v219, v179, v219
	v_add_f32_e32 v219, v254, v219
	v_cvt_pk_fp8_f32 v248, v179, v254 op_sel:[0,0,1]
	v_exp_f32_e32 v0, v94
	v_exp_f32_e32 v177, v95
	v_exp_f32_e32 v179, v96
	v_exp_f32_e32 v254, v97
	v_add_f32_e32 v219, v0, v219
	v_add_f32_e32 v219, v177, v219
	v_cvt_pk_fp8_f32 v249, v0, v177
	v_add_f32_e32 v219, v179, v219
	v_add_f32_e32 v219, v254, v219
	v_cvt_pk_fp8_f32 v249, v179, v254 op_sel:[0,0,1]
	ds_read_b128 v[90:93], v185 offset:36864
	ds_read_b128 v[94:97], v186 offset:36864
	s_waitcnt lgkmcnt(4)
	v_mfma_scale_f32_32x32x64_f8f6f4 v[114:129], v[82:89], v[138:145], v[114:129], v194, v193 op_sel_hi:[0,0,0]
	v_exp_f32_e32 v0, v66
	v_exp_f32_e32 v177, v67
	v_exp_f32_e32 v179, v68
	v_exp_f32_e32 v254, v69
	v_add_f32_e32 v219, v0, v219
	v_add_f32_e32 v219, v177, v219
	v_cvt_pk_fp8_f32 v250, v0, v177
	v_add_f32_e32 v219, v179, v219
	v_add_f32_e32 v219, v254, v219
	v_cvt_pk_fp8_f32 v250, v179, v254 op_sel:[0,0,1]
	s_waitcnt lgkmcnt(2)
	v_mfma_scale_f32_32x32x64_f8f6f4 v[98:113], v[222:229], v[138:145], v[98:113], v194, v193 op_sel_hi:[0,0,0]
	ds_read_b128 v[222:225], v185 offset:38912
	ds_read_b128 v[226:229], v186 offset:38912
	v_exp_f32_e32 v0, v70
	v_exp_f32_e32 v177, v71
	v_exp_f32_e32 v179, v72
	v_exp_f32_e32 v254, v73
	v_add_f32_e32 v219, v0, v219
	v_add_f32_e32 v219, v177, v219
	v_cvt_pk_fp8_f32 v251, v0, v177
	v_add_f32_e32 v219, v179, v219
	v_add_f32_e32 v219, v254, v219
	v_cvt_pk_fp8_f32 v251, v179, v254 op_sel:[0,0,1]
	v_exp_f32_e32 v0, v74
	v_exp_f32_e32 v177, v75
	v_exp_f32_e32 v179, v76
	v_exp_f32_e32 v254, v77
	v_add_f32_e32 v219, v0, v219
	v_add_f32_e32 v219, v177, v219
	v_cvt_pk_fp8_f32 v252, v0, v177
	v_add_f32_e32 v219, v179, v219
	v_add_f32_e32 v219, v254, v219
	v_cvt_pk_fp8_f32 v252, v179, v254 op_sel:[0,0,1]
	s_waitcnt lgkmcnt(2)
	v_mfma_scale_f32_32x32x64_f8f6f4 v[114:129], v[90:97], v[130:137], v[114:129], v194, v193 op_sel_hi:[0,0,0]
	v_exp_f32_e32 v0, v78
	v_exp_f32_e32 v177, v79
	v_exp_f32_e32 v179, v80
	v_exp_f32_e32 v254, v81
	v_add_f32_e32 v219, v0, v219
	v_add_f32_e32 v219, v177, v219
	v_cvt_pk_fp8_f32 v253, v0, v177
	v_add_f32_e32 v219, v179, v219
	v_add_f32_e32 v219, v254, v219
	v_cvt_pk_fp8_f32 v253, v179, v254 op_sel:[0,0,1]
	ds_read_b128 v[90:93], v185 offset:0
	ds_read_b128 v[94:97], v186 offset:0
	ds_read_b128 v[82:85], v185 offset:2048
	ds_read_b128 v[86:89], v186 offset:2048
	ds_read_b128 v[74:77], v185 offset:4096
	ds_read_b128 v[78:81], v186 offset:4096
	ds_read_b128 v[66:69], v185 offset:6144
	ds_read_b128 v[70:73], v186 offset:6144
	s_waitcnt lgkmcnt(8)
	v_mfma_scale_f32_32x32x64_f8f6f4 v[98:113], v[222:229], v[130:137], v[98:113], v194, v193 op_sel_hi:[0,0,0]
	v_mov_b32_e32 v0, v219
	s_nop 1
	v_permlane32_swap_b32_e32 v219, v0
	v_add_f32_e32 v219, v219, v0
	v_fma_f32 v209, v209, v218, v219
	v_max_f32_e32 v177, v114, v115
	v_max3_f32 v177, v177, v116, v117
	v_max3_f32 v177, v177, v118, v119
	v_max3_f32 v177, v177, v120, v121
	v_max3_f32 v177, v177, v122, v123
	v_max3_f32 v177, v177, v124, v125
	v_max3_f32 v177, v177, v126, v127
	v_max3_f32 v177, v177, v128, v129
	s_waitcnt lgkmcnt(6)
	v_mfma_scale_f32_32x32x64_f8f6f4 v[50:65], v[246:253], v[90:97], v[50:65], v194, v194 op_sel_hi:[0,0,0]
	s_waitcnt vmcnt(0)
	ds_write_b128 v210, v[158:161] offset:43008
	ds_write_b128 v211, v[162:165] offset:51200
	s_waitcnt lgkmcnt(6)
	v_mfma_scale_f32_32x32x64_f8f6f4 v[34:49], v[246:253], v[82:89], v[34:49], v194, v194 op_sel_hi:[0,0,0]
	s_waitcnt lgkmcnt(0)
	s_barrier
	s_waitcnt lgkmcnt(2)
	v_mfma_scale_f32_32x32x64_f8f6f4 v[18:33], v[246:253], v[74:81], v[18:33], v194, v194 op_sel_hi:[0,0,0]
	global_load_dwordx4 v[158:161], v176, s[18:19]
	global_load_dwordx4 v[162:165], v178, s[16:17]
	v_add_u32_e32 v176, 0x2000, v176
	v_add_u32_e32 v178, 0x20000, v178
	s_waitcnt lgkmcnt(0)
	v_mfma_scale_f32_32x32x64_f8f6f4 v[2:17], v[246:253], v[66:73], v[2:17], v194, v194 op_sel_hi:[0,0,0]
	v_max_f32_e32 v0, v98, v99
	v_max3_f32 v0, v0, v100, v101
	v_max3_f32 v0, v0, v102, v103
	v_max3_f32 v0, v0, v104, v105
	v_max3_f32 v0, v0, v106, v107
	v_max3_f32 v0, v0, v108, v109
	v_max3_f32 v0, v0, v110, v111
	v_max3_f32 v0, v0, v112, v113
	v_max_f32_e32 v177, v177, v0
	v_mov_b32_e32 v0, v177
	v_mov_b32_e32 v221, 1.0
	s_nop 0
	v_permlane32_swap_b32_e32 v177, v0
	v_max_f32_e32 v177, v177, v0
	v_cmp_ge_f32_e32 vcc, s90, v177
	s_cmp_eq_u64 vcc, exec
	s_cbranch_scc0 .Lmla_s0_newmax
; __device__ __forceinline__ void finishSM9(f32x16& p0, f32x16& p1, float alpha, float& l_reg, v8i32& p8) {
; #pragma unroll
;   for (int r = 0; r < 16; ++r) { p0[r] = __builtin_amdgcn_exp2f(p0[r]); p1[r] = __builtin_amdgcn_exp2f(p1[r]); }
;   float ps = 0;
; #pragma unroll
;   for (int r = 0; r < 16; ++r) ps += p0[r];
; #pragma unroll
;   for (int r = 0; r < 16; ++r) ps += p1[r];
;   { auto rr = __builtin_amdgcn_permlane32_swap(__float_as_uint(ps), __float_as_uint(ps), false, false);
;     ps = __uint_as_float(rr[0]) + __uint_as_float(rr[1]); }
;   l_reg = l_reg * alpha + ps;
; #pragma unroll
;   for (int g = 0; g < 4; ++g) {
;     int w = __builtin_amdgcn_cvt_pk_fp8_f32(p0[4 * g], p0[4 * g + 1], 0, false); p8[g] = __builtin_amdgcn_cvt_pk_fp8_f32(p0[4 * g + 2], p0[4 * g + 3], w, true);
;     int u = __builtin_amdgcn_cvt_pk_fp8_f32(p1[4 * g], p1[4 * g + 1], 0, false); p8[4 + g] = __builtin_amdgcn_cvt_pk_fp8_f32(p1[4 * g + 2], p1[4 * g + 3], u, true); }
; }
; __device__ __forceinline__ void pv8(f32x16* o, const char* Vt, const v8i32 p8, int r32, int hi) {
;   const int sw = (r32 >> 2) & 3, a0 = r32 * 64 + (((hi * 2) ^ sw) << 4), a1 = r32 * 64 + (((hi * 2 + 1) ^ sw) << 4);
; #pragma unroll
;   for (int d0 = 0; d0 < 4; ++d0) {
;     const v8i32 vf = cat8(*reinterpret_cast<const v4i32*>(Vt + d0 * 2048 + a0), *reinterpret_cast<const v4i32*>(Vt + d0 * 2048 + a1));
;     o[d0] = __builtin_amdgcn_mfma_scale_f32_32x32x64_f8f6f4(p8, vf, o[d0], 0, 0, 0, 127, 0, 127); }
; }
; __device__ __forceinline__ void qkt9(f32x16& p0, f32x16& p1, const char* Kn, const char* Kr, const v8i32* qf, const float init, int r32, int hi) {
; #pragma unroll
;   for (int r = 0; r < 16; ++r) { p0[r] = init; p1[r] = init; }
; #pragma unroll
;   for (int s = 0; s < 2; ++s) { const int c0 = s * 4 + hi * 2;
;     const v8i32 a0 = cat8(*reinterpret_cast<const v4i32*>(Kn + KN8SW(r32, c0)), *reinterpret_cast<const v4i32*>(Kn + KN8SW(r32, c0 + 1)));
;     const v8i32 a1 = cat8(*reinterpret_cast<const v4i32*>(Kn + 4096 + KN8SW(r32, c0)), *reinterpret_cast<const v4i32*>(Kn + 4096 + KN8SW(r32, c0 + 1)));
;     p0 = __builtin_amdgcn_mfma_scale_f32_32x32x64_f8f6f4(a0, qf[s], p0, 0, 0, 0, 127, 0, 124);
;     p1 = __builtin_amdgcn_mfma_scale_f32_32x32x64_f8f6f4(a1, qf[s], p1, 0, 0, 0, 127, 0, 124); }
;   { const int c0 = hi * 2;
.Lmla_s0_cont:
	ds_read_b128 v[82:85], v215 offset:51200
	ds_read_b128 v[86:89], v216 offset:51200
	ds_read_b128 v[222:225], v215 offset:55296
	ds_read_b128 v[226:229], v216 offset:55296
	v_exp_f32_e32 v0, v114
	v_exp_f32_e32 v177, v115
	v_exp_f32_e32 v179, v116
	v_exp_f32_e32 v254, v117
	v_add_f32_e32 v219, v0, v177
	v_cvt_pk_fp8_f32 v246, v0, v177
	v_add_f32_e32 v219, v179, v219
	v_add_f32_e32 v219, v254, v219
	v_cvt_pk_fp8_f32 v246, v179, v254 op_sel:[0,0,1]
	s_waitcnt lgkmcnt(2)
	v_mfma_scale_f32_32x32x64_f8f6f4 v[82:97], v[82:89], v[146:153], v[230:245], v194, v193 op_sel_hi:[0,0,0]
	v_exp_f32_e32 v0, v118
	v_exp_f32_e32 v177, v119
	v_exp_f32_e32 v179, v120
	v_exp_f32_e32 v254, v121
	v_add_f32_e32 v219, v0, v219
	v_add_f32_e32 v219, v177, v219
	v_cvt_pk_fp8_f32 v247, v0, v177
	v_add_f32_e32 v219, v179, v219
	v_add_f32_e32 v219, v254, v219
	v_cvt_pk_fp8_f32 v247, v179, v254 op_sel:[0,0,1]
	ds_read_b128 v[114:117], v213 offset:51200
	ds_read_b128 v[118:121], v214 offset:51200
	s_waitcnt lgkmcnt(2)
	v_mfma_scale_f32_32x32x64_f8f6f4 v[66:81], v[222:229], v[146:153], v[230:245], v194, v193 op_sel_hi:[0,0,0]
	ds_read_b128 v[222:225], v213 offset:55296
	ds_read_b128 v[226:229], v214 offset:55296
	v_exp_f32_e32 v0, v122
	v_exp_f32_e32 v177, v123
	v_exp_f32_e32 v179, v124
	v_exp_f32_e32 v254, v125
	v_add_f32_e32 v219, v0, v219
	v_add_f32_e32 v219, v177, v219
	v_cvt_pk_fp8_f32 v248, v0, v177
	v_add_f32_e32 v219, v179, v219
	v_add_f32_e32 v219, v254, v219
	v_cvt_pk_fp8_f32 v248, v179, v254 op_sel:[0,0,1]
	v_exp_f32_e32 v0, v126
	v_exp_f32_e32 v177, v127
	v_exp_f32_e32 v179, v128
	v_exp_f32_e32 v254, v129
	v_add_f32_e32 v219, v0, v219
	v_add_f32_e32 v219, v177, v219
	v_cvt_pk_fp8_f32 v249, v0, v177
	v_add_f32_e32 v219, v179, v219
	v_add_f32_e32 v219, v254, v219
	v_cvt_pk_fp8_f32 v249, v179, v254 op_sel:[0,0,1]
	ds_read_b128 v[122:125], v185 offset:59392
	ds_read_b128 v[126:129], v186 offset:59392
	s_waitcnt lgkmcnt(4)
	v_mfma_scale_f32_32x32x64_f8f6f4 v[82:97], v[114:121], v[138:145], v[82:97], v194, v193 op_sel_hi:[0,0,0]
	v_exp_f32_e32 v0, v98
	v_exp_f32_e32 v177, v99
	v_exp_f32_e32 v179, v100
	v_exp_f32_e32 v254, v101
	v_add_f32_e32 v219, v0, v219
	v_add_f32_e32 v219, v177, v219
	v_cvt_pk_fp8_f32 v250, v0, v177
	v_add_f32_e32 v219, v179, v219
	v_add_f32_e32 v219, v254, v219
	v_cvt_pk_fp8_f32 v250, v179, v254 op_sel:[0,0,1]
	s_waitcnt lgkmcnt(2)
	v_mfma_scale_f32_32x32x64_f8f6f4 v[66:81], v[222:229], v[138:145], v[66:81], v194, v193 op_sel_hi:[0,0,0]
	ds_read_b128 v[222:225], v185 offset:61440
	ds_read_b128 v[226:229], v186 offset:61440
	v_exp_f32_e32 v0, v102
	v_exp_f32_e32 v177, v103
	v_exp_f32_e32 v179, v104
	v_exp_f32_e32 v254, v105
	v_add_f32_e32 v219, v0, v219
	v_add_f32_e32 v219, v177, v219
	v_cvt_pk_fp8_f32 v251, v0, v177
	v_add_f32_e32 v219, v179, v219
	v_add_f32_e32 v219, v254, v219
	v_cvt_pk_fp8_f32 v251, v179, v254 op_sel:[0,0,1]
	v_exp_f32_e32 v0, v106
	v_exp_f32_e32 v177, v107
	v_exp_f32_e32 v179, v108
	v_exp_f32_e32 v254, v109
	v_add_f32_e32 v219, v0, v219
	v_add_f32_e32 v219, v177, v219
	v_cvt_pk_fp8_f32 v252, v0, v177
	v_add_f32_e32 v219, v179, v219
	v_add_f32_e32 v219, v254, v219
	v_cvt_pk_fp8_f32 v252, v179, v254 op_sel:[0,0,1]
	s_waitcnt lgkmcnt(2)
	v_mfma_scale_f32_32x32x64_f8f6f4 v[82:97], v[122:129], v[130:137], v[82:97], v194, v193 op_sel_hi:[0,0,0]
	v_exp_f32_e32 v0, v110
	v_exp_f32_e32 v177, v111
	v_exp_f32_e32 v179, v112
	v_exp_f32_e32 v254, v113
	v_add_f32_e32 v219, v0, v219
	v_add_f32_e32 v219, v177, v219
	v_cvt_pk_fp8_f32 v253, v0, v177
	v_add_f32_e32 v219, v179, v219
	v_add_f32_e32 v219, v254, v219
	v_cvt_pk_fp8_f32 v253, v179, v254 op_sel:[0,0,1]
	ds_read_b128 v[122:125], v185 offset:8192
	ds_read_b128 v[126:129], v186 offset:8192
	ds_read_b128 v[114:117], v185 offset:10240
	ds_read_b128 v[118:121], v186 offset:10240
	ds_read_b128 v[106:109], v185 offset:12288
	ds_read_b128 v[110:113], v186 offset:12288
	ds_read_b128 v[98:101], v185 offset:14336
	ds_read_b128 v[102:105], v186 offset:14336
	s_waitcnt lgkmcnt(8)
	v_mfma_scale_f32_32x32x64_f8f6f4 v[66:81], v[222:229], v[130:137], v[66:81], v194, v193 op_sel_hi:[0,0,0]
	v_mov_b32_e32 v0, v219
	s_nop 1
	v_permlane32_swap_b32_e32 v219, v0
	v_add_f32_e32 v219, v219, v0
	v_fma_f32 v209, v209, v221, v219
	v_max_f32_e32 v177, v82, v83
	v_max3_f32 v177, v177, v84, v85
	v_max3_f32 v177, v177, v86, v87
	v_max3_f32 v177, v177, v88, v89
	v_max3_f32 v177, v177, v90, v91
	v_max3_f32 v177, v177, v92, v93
	v_max3_f32 v177, v177, v94, v95
	v_max3_f32 v177, v177, v96, v97
	s_waitcnt lgkmcnt(6)
	v_mfma_scale_f32_32x32x64_f8f6f4 v[50:65], v[246:253], v[122:129], v[50:65], v194, v194 op_sel_hi:[0,0,0]
	s_waitcnt vmcnt(0)
	ds_write_b128 v210, v[158:161]
	ds_write_b128 v211, v[162:165] offset:16384
	s_waitcnt lgkmcnt(6)
	v_mfma_scale_f32_32x32x64_f8f6f4 v[34:49], v[246:253], v[114:121], v[34:49], v194, v194 op_sel_hi:[0,0,0]
	s_waitcnt lgkmcnt(0)
	s_barrier
	s_waitcnt lgkmcnt(2)
	v_mfma_scale_f32_32x32x64_f8f6f4 v[18:33], v[246:253], v[106:113], v[18:33], v194, v194 op_sel_hi:[0,0,0]
	global_load_dwordx4 v[158:161], v176, s[18:19]
	global_load_dwordx4 v[162:165], v178, s[16:17]
	v_add_u32_e32 v176, 0x2000, v176
	v_add_u32_e32 v178, 0x20000, v178
	s_waitcnt lgkmcnt(0)
	v_mfma_scale_f32_32x32x64_f8f6f4 v[2:17], v[246:253], v[98:105], v[2:17], v194, v194 op_sel_hi:[0,0,0]
	v_max_f32_e32 v0, v66, v67
	v_max3_f32 v0, v0, v68, v69
	v_max3_f32 v0, v0, v70, v71
	v_max3_f32 v0, v0, v72, v73
	v_max3_f32 v0, v0, v74, v75
	v_max3_f32 v0, v0, v76, v77
	v_max3_f32 v0, v0, v78, v79
	v_max3_f32 v0, v0, v80, v81
	v_max_f32_e32 v177, v177, v0
	v_mov_b32_e32 v0, v177
	v_mov_b32_e32 v218, 1.0
	s_nop 0
	v_permlane32_swap_b32_e32 v177, v0
	v_max_f32_e32 v177, v177, v0
	v_cmp_ge_f32_e32 vcc, s90, v177
	s_cmp_eq_u64 vcc, exec
	s_cbranch_scc0 .Lmla_s1_newmax
; __device__ __forceinline__ void finishSM9(f32x16& p0, f32x16& p1, float alpha, float& l_reg, v8i32& p8) {
; #pragma unroll
;   for (int r = 0; r < 16; ++r) { p0[r] = __builtin_amdgcn_exp2f(p0[r]); p1[r] = __builtin_amdgcn_exp2f(p1[r]); }
;   float ps = 0;
; #pragma unroll
;   for (int r = 0; r < 16; ++r) ps += p0[r];
; #pragma unroll
;   for (int r = 0; r < 16; ++r) ps += p1[r];
;   { auto rr = __builtin_amdgcn_permlane32_swap(__float_as_uint(ps), __float_as_uint(ps), false, false);
;     ps = __uint_as_float(rr[0]) + __uint_as_float(rr[1]); }
;   l_reg = l_reg * alpha + ps;
; #pragma unroll
;   for (int g = 0; g < 4; ++g) {
;     int w = __builtin_amdgcn_cvt_pk_fp8_f32(p0[4 * g], p0[4 * g + 1], 0, false); p8[g] = __builtin_amdgcn_cvt_pk_fp8_f32(p0[4 * g + 2], p0[4 * g + 3], w, true);
;     int u = __builtin_amdgcn_cvt_pk_fp8_f32(p1[4 * g], p1[4 * g + 1], 0, false); p8[4 + g] = __builtin_amdgcn_cvt_pk_fp8_f32(p1[4 * g + 2], p1[4 * g + 3], u, true); }
; }
; __device__ __forceinline__ void pv8(f32x16* o, const char* Vt, const v8i32 p8, int r32, int hi) {
;   const int sw = (r32 >> 2) & 3, a0 = r32 * 64 + (((hi * 2) ^ sw) << 4), a1 = r32 * 64 + (((hi * 2 + 1) ^ sw) << 4);
; #pragma unroll
;   for (int d0 = 0; d0 < 4; ++d0) {
;     const v8i32 vf = cat8(*reinterpret_cast<const v4i32*>(Vt + d0 * 2048 + a0), *reinterpret_cast<const v4i32*>(Vt + d0 * 2048 + a1));
;     o[d0] = __builtin_amdgcn_mfma_scale_f32_32x32x64_f8f6f4(p8, vf, o[d0], 0, 0, 0, 127, 0, 127); }
; }
; __device__ __forceinline__ void qkt9(f32x16& p0, f32x16& p1, const char* Kn, const char* Kr, const v8i32* qf, const float init, int r32, int hi) {
; #pragma unroll
;   for (int r = 0; r < 16; ++r) { p0[r] = init; p1[r] = init; }
; #pragma unroll
;   for (int s = 0; s < 2; ++s) { const int c0 = s * 4 + hi * 2;
;     const v8i32 a0 = cat8(*reinterpret_cast<const v4i32*>(Kn + KN8SW(r32, c0)), *reinterpret_cast<const v4i32*>(Kn + KN8SW(r32, c0 + 1)));
;     const v8i32 a1 = cat8(*reinterpret_cast<const v4i32*>(Kn + 4096 + KN8SW(r32, c0)), *reinterpret_cast<const v4i32*>(Kn + 4096 + KN8SW(r32, c0 + 1)));
;     p0 = __builtin_amdgcn_mfma_scale_f32_32x32x64_f8f6f4(a0, qf[s], p0, 0, 0, 0, 127, 0, 124);
;     p1 = __builtin_amdgcn_mfma_scale_f32_32x32x64_f8f6f4(a1, qf[s], p1, 0, 0, 0, 127, 0, 124); }
;   { const int c0 = hi * 2;
.Lmla_s1_cont:
	ds_read_b128 v[114:117], v215 offset:16384
	ds_read_b128 v[118:121], v216 offset:16384
	ds_read_b128 v[222:225], v215 offset:20480
	ds_read_b128 v[226:229], v216 offset:20480
	v_exp_f32_e32 v0, v82
	v_exp_f32_e32 v177, v83
	v_exp_f32_e32 v179, v84
	v_exp_f32_e32 v254, v85
	v_add_f32_e32 v219, v0, v177
	v_cvt_pk_fp8_f32 v246, v0, v177
	v_add_f32_e32 v219, v179, v219
	v_add_f32_e32 v219, v254, v219
	v_cvt_pk_fp8_f32 v246, v179, v254 op_sel:[0,0,1]
	s_waitcnt lgkmcnt(2)
	v_mfma_scale_f32_32x32x64_f8f6f4 v[114:129], v[114:121], v[146:153], v[230:245], v194, v193 op_sel_hi:[0,0,0]
	v_exp_f32_e32 v0, v86
	v_exp_f32_e32 v177, v87
	v_exp_f32_e32 v179, v88
	v_exp_f32_e32 v254, v89
	v_add_f32_e32 v219, v0, v219
	v_add_f32_e32 v219, v177, v219
	v_cvt_pk_fp8_f32 v247, v0, v177
	v_add_f32_e32 v219, v179, v219
	v_add_f32_e32 v219, v254, v219
	v_cvt_pk_fp8_f32 v247, v179, v254 op_sel:[0,0,1]
	ds_read_b128 v[82:85], v213 offset:16384
	ds_read_b128 v[86:89], v214 offset:16384
	s_waitcnt lgkmcnt(2)
	v_mfma_scale_f32_32x32x64_f8f6f4 v[98:113], v[222:229], v[146:153], v[230:245], v194, v193 op_sel_hi:[0,0,0]
	ds_read_b128 v[222:225], v213 offset:20480
	ds_read_b128 v[226:229], v214 offset:20480
	v_exp_f32_e32 v0, v90
	v_exp_f32_e32 v177, v91
	v_exp_f32_e32 v179, v92
	v_exp_f32_e32 v254, v93
	v_add_f32_e32 v219, v0, v219
	v_add_f32_e32 v219, v177, v219
	v_cvt_pk_fp8_f32 v248, v0, v177
	v_add_f32_e32 v219, v179, v219
	v_add_f32_e32 v219, v254, v219
	v_cvt_pk_fp8_f32 v248, v179, v254 op_sel:[0,0,1]
	v_exp_f32_e32 v0, v94
	v_exp_f32_e32 v177, v95
	v_exp_f32_e32 v179, v96
	v_exp_f32_e32 v254, v97
	v_add_f32_e32 v219, v0, v219
	v_add_f32_e32 v219, v177, v219
	v_cvt_pk_fp8_f32 v249, v0, v177
	v_add_f32_e32 v219, v179, v219
	v_add_f32_e32 v219, v254, v219
	v_cvt_pk_fp8_f32 v249, v179, v254 op_sel:[0,0,1]
	ds_read_b128 v[90:93], v185 offset:32768
	ds_read_b128 v[94:97], v186 offset:32768
	s_waitcnt lgkmcnt(4)
	v_mfma_scale_f32_32x32x64_f8f6f4 v[114:129], v[82:89], v[138:145], v[114:129], v194, v193 op_sel_hi:[0,0,0]
	v_exp_f32_e32 v0, v66
	v_exp_f32_e32 v177, v67
	v_exp_f32_e32 v179, v68
	v_exp_f32_e32 v254, v69
	v_add_f32_e32 v219, v0, v219
	v_add_f32_e32 v219, v177, v219
	v_cvt_pk_fp8_f32 v250, v0, v177
	v_add_f32_e32 v219, v179, v219
	v_add_f32_e32 v219, v254, v219
	v_cvt_pk_fp8_f32 v250, v179, v254 op_sel:[0,0,1]
	s_waitcnt lgkmcnt(2)
	v_mfma_scale_f32_32x32x64_f8f6f4 v[98:113], v[222:229], v[138:145], v[98:113], v194, v193 op_sel_hi:[0,0,0]
	ds_read_b128 v[222:225], v185 offset:34816
	ds_read_b128 v[226:229], v186 offset:34816
	v_exp_f32_e32 v0, v70
	v_exp_f32_e32 v177, v71
	v_exp_f32_e32 v179, v72
	v_exp_f32_e32 v254, v73
	v_add_f32_e32 v219, v0, v219
	v_add_f32_e32 v219, v177, v219
	v_cvt_pk_fp8_f32 v251, v0, v177
	v_add_f32_e32 v219, v179, v219
	v_add_f32_e32 v219, v254, v219
	v_cvt_pk_fp8_f32 v251, v179, v254 op_sel:[0,0,1]
	v_exp_f32_e32 v0, v74
	v_exp_f32_e32 v177, v75
	v_exp_f32_e32 v179, v76
	v_exp_f32_e32 v254, v77
	v_add_f32_e32 v219, v0, v219
	v_add_f32_e32 v219, v177, v219
	v_cvt_pk_fp8_f32 v252, v0, v177
	v_add_f32_e32 v219, v179, v219
	v_add_f32_e32 v219, v254, v219
	v_cvt_pk_fp8_f32 v252, v179, v254 op_sel:[0,0,1]
	s_waitcnt lgkmcnt(2)
	v_mfma_scale_f32_32x32x64_f8f6f4 v[114:129], v[90:97], v[130:137], v[114:129], v194, v193 op_sel_hi:[0,0,0]
	v_exp_f32_e32 v0, v78
	v_exp_f32_e32 v177, v79
	v_exp_f32_e32 v179, v80
	v_exp_f32_e32 v254, v81
	v_add_f32_e32 v219, v0, v219
	v_add_f32_e32 v219, v177, v219
	v_cvt_pk_fp8_f32 v253, v0, v177
	v_add_f32_e32 v219, v179, v219
	v_add_f32_e32 v219, v254, v219
	v_cvt_pk_fp8_f32 v253, v179, v254 op_sel:[0,0,1]
	ds_read_b128 v[90:93], v185 offset:43008
	ds_read_b128 v[94:97], v186 offset:43008
	ds_read_b128 v[82:85], v185 offset:45056
	ds_read_b128 v[86:89], v186 offset:45056
	ds_read_b128 v[74:77], v185 offset:47104
	ds_read_b128 v[78:81], v186 offset:47104
	ds_read_b128 v[66:69], v185 offset:49152
	ds_read_b128 v[70:73], v186 offset:49152
	s_waitcnt lgkmcnt(8)
	v_mfma_scale_f32_32x32x64_f8f6f4 v[98:113], v[222:229], v[130:137], v[98:113], v194, v193 op_sel_hi:[0,0,0]
	v_mov_b32_e32 v0, v219
	s_nop 1
	v_permlane32_swap_b32_e32 v219, v0
	v_add_f32_e32 v219, v219, v0
	v_fma_f32 v209, v209, v218, v219
	v_max_f32_e32 v177, v114, v115
	v_max3_f32 v177, v177, v116, v117
	v_max3_f32 v177, v177, v118, v119
	v_max3_f32 v177, v177, v120, v121
	v_max3_f32 v177, v177, v122, v123
	v_max3_f32 v177, v177, v124, v125
	v_max3_f32 v177, v177, v126, v127
	v_max3_f32 v177, v177, v128, v129
	s_waitcnt lgkmcnt(6)
	v_mfma_scale_f32_32x32x64_f8f6f4 v[50:65], v[246:253], v[90:97], v[50:65], v194, v194 op_sel_hi:[0,0,0]
	s_waitcnt vmcnt(0)
	ds_write_b128 v210, v[158:161] offset:8192
	ds_write_b128 v211, v[162:165] offset:24576
	s_waitcnt lgkmcnt(6)
	v_mfma_scale_f32_32x32x64_f8f6f4 v[34:49], v[246:253], v[82:89], v[34:49], v194, v194 op_sel_hi:[0,0,0]
	s_waitcnt lgkmcnt(0)
	s_barrier
	s_waitcnt lgkmcnt(2)
	v_mfma_scale_f32_32x32x64_f8f6f4 v[18:33], v[246:253], v[74:81], v[18:33], v194, v194 op_sel_hi:[0,0,0]
	global_load_dwordx4 v[158:161], v176, s[18:19]
	global_load_dwordx4 v[162:165], v178, s[16:17]
	v_add_u32_e32 v176, 0x2000, v176
	v_add_u32_e32 v178, 0x20000, v178
	s_waitcnt lgkmcnt(0)
	v_mfma_scale_f32_32x32x64_f8f6f4 v[2:17], v[246:253], v[66:73], v[2:17], v194, v194 op_sel_hi:[0,0,0]
	v_max_f32_e32 v0, v98, v99
	v_max3_f32 v0, v0, v100, v101
	v_max3_f32 v0, v0, v102, v103
	v_max3_f32 v0, v0, v104, v105
	v_max3_f32 v0, v0, v106, v107
	v_max3_f32 v0, v0, v108, v109
	v_max3_f32 v0, v0, v110, v111
	v_max3_f32 v0, v0, v112, v113
	v_max_f32_e32 v177, v177, v0
	v_mov_b32_e32 v0, v177
	v_mov_b32_e32 v221, 1.0
	s_nop 0
	v_permlane32_swap_b32_e32 v177, v0
	v_max_f32_e32 v177, v177, v0
	v_cmp_ge_f32_e32 vcc, s90, v177
	s_cmp_eq_u64 vcc, exec
	s_cbranch_scc0 .Lmla_s2_newmax
; __device__ __forceinline__ void finishSM9(f32x16& p0, f32x16& p1, float alpha, float& l_reg, v8i32& p8) {
; #pragma unroll
;   for (int r = 0; r < 16; ++r) { p0[r] = __builtin_amdgcn_exp2f(p0[r]); p1[r] = __builtin_amdgcn_exp2f(p1[r]); }
;   float ps = 0;
; #pragma unroll
;   for (int r = 0; r < 16; ++r) ps += p0[r];
; #pragma unroll
;   for (int r = 0; r < 16; ++r) ps += p1[r];
;   { auto rr = __builtin_amdgcn_permlane32_swap(__float_as_uint(ps), __float_as_uint(ps), false, false);
;     ps = __uint_as_float(rr[0]) + __uint_as_float(rr[1]); }
;   l_reg = l_reg * alpha + ps;
; #pragma unroll
;   for (int g = 0; g < 4; ++g) {
;     int w = __builtin_amdgcn_cvt_pk_fp8_f32(p0[4 * g], p0[4 * g + 1], 0, false); p8[g] = __builtin_amdgcn_cvt_pk_fp8_f32(p0[4 * g + 2], p0[4 * g + 3], w, true);
;     int u = __builtin_amdgcn_cvt_pk_fp8_f32(p1[4 * g], p1[4 * g + 1], 0, false); p8[4 + g] = __builtin_amdgcn_cvt_pk_fp8_f32(p1[4 * g + 2], p1[4 * g + 3], u, true); }
; }
; __device__ __forceinline__ void pv8(f32x16* o, const char* Vt, const v8i32 p8, int r32, int hi) {
;   const int sw = (r32 >> 2) & 3, a0 = r32 * 64 + (((hi * 2) ^ sw) << 4), a1 = r32 * 64 + (((hi * 2 + 1) ^ sw) << 4);
; #pragma unroll
;   for (int d0 = 0; d0 < 4; ++d0) {
;     const v8i32 vf = cat8(*reinterpret_cast<const v4i32*>(Vt + d0 * 2048 + a0), *reinterpret_cast<const v4i32*>(Vt + d0 * 2048 + a1));
;     o[d0] = __builtin_amdgcn_mfma_scale_f32_32x32x64_f8f6f4(p8, vf, o[d0], 0, 0, 0, 127, 0, 127); }
; }
; __device__ __forceinline__ void qkt9(f32x16& p0, f32x16& p1, const char* Kn, const char* Kr, const v8i32* qf, const float init, int r32, int hi) {
; #pragma unroll
;   for (int r = 0; r < 16; ++r) { p0[r] = init; p1[r] = init; }
; #pragma unroll
;   for (int s = 0; s < 2; ++s) { const int c0 = s * 4 + hi * 2;
;     const v8i32 a0 = cat8(*reinterpret_cast<const v4i32*>(Kn + KN8SW(r32, c0)), *reinterpret_cast<const v4i32*>(Kn + KN8SW(r32, c0 + 1)));
;     const v8i32 a1 = cat8(*reinterpret_cast<const v4i32*>(Kn + 4096 + KN8SW(r32, c0)), *reinterpret_cast<const v4i32*>(Kn + 4096 + KN8SW(r32, c0 + 1)));
;     p0 = __builtin_amdgcn_mfma_scale_f32_32x32x64_f8f6f4(a0, qf[s], p0, 0, 0, 0, 127, 0, 124);
;     p1 = __builtin_amdgcn_mfma_scale_f32_32x32x64_f8f6f4(a1, qf[s], p1, 0, 0, 0, 127, 0, 124); }
;   { const int c0 = hi * 2;
.Lmla_s2_cont:
	ds_read_b128 v[82:85], v215 offset:24576
	ds_read_b128 v[86:89], v216 offset:24576
	ds_read_b128 v[222:225], v215 offset:28672
	ds_read_b128 v[226:229], v216 offset:28672
	v_exp_f32_e32 v0, v114
	v_exp_f32_e32 v177, v115
	v_exp_f32_e32 v179, v116
	v_exp_f32_e32 v254, v117
	v_add_f32_e32 v219, v0, v177
	v_cvt_pk_fp8_f32 v246, v0, v177
	v_add_f32_e32 v219, v179, v219
	v_add_f32_e32 v219, v254, v219
	v_cvt_pk_fp8_f32 v246, v179, v254 op_sel:[0,0,1]
	s_waitcnt lgkmcnt(2)
	v_mfma_scale_f32_32x32x64_f8f6f4 v[82:97], v[82:89], v[146:153], v[230:245], v194, v193 op_sel_hi:[0,0,0]
	v_exp_f32_e32 v0, v118
	v_exp_f32_e32 v177, v119
	v_exp_f32_e32 v179, v120
	v_exp_f32_e32 v254, v121
	v_add_f32_e32 v219, v0, v219
	v_add_f32_e32 v219, v177, v219
	v_cvt_pk_fp8_f32 v247, v0, v177
	v_add_f32_e32 v219, v179, v219
	v_add_f32_e32 v219, v254, v219
	v_cvt_pk_fp8_f32 v247, v179, v254 op_sel:[0,0,1]
	ds_read_b128 v[114:117], v213 offset:24576
	ds_read_b128 v[118:121], v214 offset:24576
	s_waitcnt lgkmcnt(2)
	v_mfma_scale_f32_32x32x64_f8f6f4 v[66:81], v[222:229], v[146:153], v[230:245], v194, v193 op_sel_hi:[0,0,0]
	ds_read_b128 v[222:225], v213 offset:28672
	ds_read_b128 v[226:229], v214 offset:28672
	v_exp_f32_e32 v0, v122
	v_exp_f32_e32 v177, v123
	v_exp_f32_e32 v179, v124
	v_exp_f32_e32 v254, v125
	v_add_f32_e32 v219, v0, v219
	v_add_f32_e32 v219, v177, v219
	v_cvt_pk_fp8_f32 v248, v0, v177
	v_add_f32_e32 v219, v179, v219
	v_add_f32_e32 v219, v254, v219
	v_cvt_pk_fp8_f32 v248, v179, v254 op_sel:[0,0,1]
	v_exp_f32_e32 v0, v126
	v_exp_f32_e32 v177, v127
	v_exp_f32_e32 v179, v128
	v_exp_f32_e32 v254, v129
	v_add_f32_e32 v219, v0, v219
	v_add_f32_e32 v219, v177, v219
	v_cvt_pk_fp8_f32 v249, v0, v177
	v_add_f32_e32 v219, v179, v219
	v_add_f32_e32 v219, v254, v219
	v_cvt_pk_fp8_f32 v249, v179, v254 op_sel:[0,0,1]
	ds_read_b128 v[122:125], v185 offset:36864
	ds_read_b128 v[126:129], v186 offset:36864
	s_waitcnt lgkmcnt(4)
	v_mfma_scale_f32_32x32x64_f8f6f4 v[82:97], v[114:121], v[138:145], v[82:97], v194, v193 op_sel_hi:[0,0,0]
	v_exp_f32_e32 v0, v98
	v_exp_f32_e32 v177, v99
	v_exp_f32_e32 v179, v100
	v_exp_f32_e32 v254, v101
	v_add_f32_e32 v219, v0, v219
	v_add_f32_e32 v219, v177, v219
	v_cvt_pk_fp8_f32 v250, v0, v177
	v_add_f32_e32 v219, v179, v219
	v_add_f32_e32 v219, v254, v219
	v_cvt_pk_fp8_f32 v250, v179, v254 op_sel:[0,0,1]
	s_waitcnt lgkmcnt(2)
	v_mfma_scale_f32_32x32x64_f8f6f4 v[66:81], v[222:229], v[138:145], v[66:81], v194, v193 op_sel_hi:[0,0,0]
	ds_read_b128 v[222:225], v185 offset:38912
	ds_read_b128 v[226:229], v186 offset:38912
	v_exp_f32_e32 v0, v102
	v_exp_f32_e32 v177, v103
	v_exp_f32_e32 v179, v104
	v_exp_f32_e32 v254, v105
	v_add_f32_e32 v219, v0, v219
	v_add_f32_e32 v219, v177, v219
	v_cvt_pk_fp8_f32 v251, v0, v177
	v_add_f32_e32 v219, v179, v219
	v_add_f32_e32 v219, v254, v219
	v_cvt_pk_fp8_f32 v251, v179, v254 op_sel:[0,0,1]
	v_exp_f32_e32 v0, v106
	v_exp_f32_e32 v177, v107
	v_exp_f32_e32 v179, v108
	v_exp_f32_e32 v254, v109
	v_add_f32_e32 v219, v0, v219
	v_add_f32_e32 v219, v177, v219
	v_cvt_pk_fp8_f32 v252, v0, v177
	v_add_f32_e32 v219, v179, v219
	v_add_f32_e32 v219, v254, v219
	v_cvt_pk_fp8_f32 v252, v179, v254 op_sel:[0,0,1]
	s_waitcnt lgkmcnt(2)
	v_mfma_scale_f32_32x32x64_f8f6f4 v[82:97], v[122:129], v[130:137], v[82:97], v194, v193 op_sel_hi:[0,0,0]
	v_exp_f32_e32 v0, v110
	v_exp_f32_e32 v177, v111
	v_exp_f32_e32 v179, v112
	v_exp_f32_e32 v254, v113
	v_add_f32_e32 v219, v0, v219
	v_add_f32_e32 v219, v177, v219
	v_cvt_pk_fp8_f32 v253, v0, v177
	v_add_f32_e32 v219, v179, v219
	v_add_f32_e32 v219, v254, v219
	v_cvt_pk_fp8_f32 v253, v179, v254 op_sel:[0,0,1]
	ds_read_b128 v[122:125], v185 offset:0
	ds_read_b128 v[126:129], v186 offset:0
	ds_read_b128 v[114:117], v185 offset:2048
	ds_read_b128 v[118:121], v186 offset:2048
	ds_read_b128 v[106:109], v185 offset:4096
	ds_read_b128 v[110:113], v186 offset:4096
	ds_read_b128 v[98:101], v185 offset:6144
	ds_read_b128 v[102:105], v186 offset:6144
	s_waitcnt lgkmcnt(8)
	v_mfma_scale_f32_32x32x64_f8f6f4 v[66:81], v[222:229], v[130:137], v[66:81], v194, v193 op_sel_hi:[0,0,0]
	v_mov_b32_e32 v0, v219
	s_nop 1
	v_permlane32_swap_b32_e32 v219, v0
	v_add_f32_e32 v219, v219, v0
	v_fma_f32 v209, v209, v221, v219
	v_max_f32_e32 v177, v82, v83
	v_max3_f32 v177, v177, v84, v85
	v_max3_f32 v177, v177, v86, v87
	v_max3_f32 v177, v177, v88, v89
	v_max3_f32 v177, v177, v90, v91
	v_max3_f32 v177, v177, v92, v93
	v_max3_f32 v177, v177, v94, v95
	v_max3_f32 v177, v177, v96, v97
	s_waitcnt lgkmcnt(6)
	v_mfma_scale_f32_32x32x64_f8f6f4 v[50:65], v[246:253], v[122:129], v[50:65], v194, v194 op_sel_hi:[0,0,0]
	s_waitcnt vmcnt(0)
	ds_write_b128 v210, v[158:161] offset:43008
	ds_write_b128 v211, v[162:165] offset:51200
	s_waitcnt lgkmcnt(6)
	v_mfma_scale_f32_32x32x64_f8f6f4 v[34:49], v[246:253], v[114:121], v[34:49], v194, v194 op_sel_hi:[0,0,0]
	s_waitcnt lgkmcnt(0)
	s_barrier
	s_waitcnt lgkmcnt(2)
	v_mfma_scale_f32_32x32x64_f8f6f4 v[18:33], v[246:253], v[106:113], v[18:33], v194, v194 op_sel_hi:[0,0,0]
	global_load_dwordx4 v[158:161], v176, s[18:19]
	global_load_dwordx4 v[162:165], v178, s[16:17]
	v_add_u32_e32 v176, 0x2000, v176
	v_add_u32_e32 v178, 0x20000, v178
	s_waitcnt lgkmcnt(0)
	v_mfma_scale_f32_32x32x64_f8f6f4 v[2:17], v[246:253], v[98:105], v[2:17], v194, v194 op_sel_hi:[0,0,0]
	v_max_f32_e32 v0, v66, v67
	v_max3_f32 v0, v0, v68, v69
	v_max3_f32 v0, v0, v70, v71
	v_max3_f32 v0, v0, v72, v73
	v_max3_f32 v0, v0, v74, v75
	v_max3_f32 v0, v0, v76, v77
	v_max3_f32 v0, v0, v78, v79
	v_max3_f32 v0, v0, v80, v81
	v_max_f32_e32 v177, v177, v0
	v_mov_b32_e32 v0, v177
	v_mov_b32_e32 v218, 1.0
	s_nop 0
	v_permlane32_swap_b32_e32 v177, v0
	v_max_f32_e32 v177, v177, v0
	v_cmp_ge_f32_e32 vcc, s90, v177
	s_cmp_eq_u64 vcc, exec
	s_cbranch_scc0 .Lmla_s3_newmax
; __device__ __forceinline__ void finishSM9(f32x16& p0, f32x16& p1, float alpha, float& l_reg, v8i32& p8) {
; #pragma unroll
;   for (int r = 0; r < 16; ++r) { p0[r] = __builtin_amdgcn_exp2f(p0[r]); p1[r] = __builtin_amdgcn_exp2f(p1[r]); }
;   float ps = 0;
; #pragma unroll
;   for (int r = 0; r < 16; ++r) ps += p0[r];
; #pragma unroll
;   for (int r = 0; r < 16; ++r) ps += p1[r];
;   { auto rr = __builtin_amdgcn_permlane32_swap(__float_as_uint(ps), __float_as_uint(ps), false, false);
;     ps = __uint_as_float(rr[0]) + __uint_as_float(rr[1]); }
;   l_reg = l_reg * alpha + ps;
; #pragma unroll
;   for (int g = 0; g < 4; ++g) {
;     int w = __builtin_amdgcn_cvt_pk_fp8_f32(p0[4 * g], p0[4 * g + 1], 0, false); p8[g] = __builtin_amdgcn_cvt_pk_fp8_f32(p0[4 * g + 2], p0[4 * g + 3], w, true);
;     int u = __builtin_amdgcn_cvt_pk_fp8_f32(p1[4 * g], p1[4 * g + 1], 0, false); p8[4 + g] = __builtin_amdgcn_cvt_pk_fp8_f32(p1[4 * g + 2], p1[4 * g + 3], u, true); }
; }
; __device__ __forceinline__ void pv8(f32x16* o, const char* Vt, const v8i32 p8, int r32, int hi) {
;   const int sw = (r32 >> 2) & 3, a0 = r32 * 64 + (((hi * 2) ^ sw) << 4), a1 = r32 * 64 + (((hi * 2 + 1) ^ sw) << 4);
; #pragma unroll
;   for (int d0 = 0; d0 < 4; ++d0) {
;     const v8i32 vf = cat8(*reinterpret_cast<const v4i32*>(Vt + d0 * 2048 + a0), *reinterpret_cast<const v4i32*>(Vt + d0 * 2048 + a1));
;     o[d0] = __builtin_amdgcn_mfma_scale_f32_32x32x64_f8f6f4(p8, vf, o[d0], 0, 0, 0, 127, 0, 127); }
; }
; __device__ __forceinline__ void qkt9(f32x16& p0, f32x16& p1, const char* Kn, const char* Kr, const v8i32* qf, const float init, int r32, int hi) {
; #pragma unroll
;   for (int r = 0; r < 16; ++r) { p0[r] = init; p1[r] = init; }
; #pragma unroll
;   for (int s = 0; s < 2; ++s) { const int c0 = s * 4 + hi * 2;
;     const v8i32 a0 = cat8(*reinterpret_cast<const v4i32*>(Kn + KN8SW(r32, c0)), *reinterpret_cast<const v4i32*>(Kn + KN8SW(r32, c0 + 1)));
;     const v8i32 a1 = cat8(*reinterpret_cast<const v4i32*>(Kn + 4096 + KN8SW(r32, c0)), *reinterpret_cast<const v4i32*>(Kn + 4096 + KN8SW(r32, c0 + 1)));
;     p0 = __builtin_amdgcn_mfma_scale_f32_32x32x64_f8f6f4(a0, qf[s], p0, 0, 0, 0, 127, 0, 124);
;     p1 = __builtin_amdgcn_mfma_scale_f32_32x32x64_f8f6f4(a1, qf[s], p1, 0, 0, 0, 127, 0, 124); }
;   { const int c0 = hi * 2;
.Lmla_s3_cont:
	ds_read_b128 v[114:117], v215 offset:51200
	ds_read_b128 v[118:121], v216 offset:51200
	ds_read_b128 v[222:225], v215 offset:55296
	ds_read_b128 v[226:229], v216 offset:55296
	v_exp_f32_e32 v0, v82
	v_exp_f32_e32 v177, v83
	v_exp_f32_e32 v179, v84
	v_exp_f32_e32 v254, v85
	v_add_f32_e32 v219, v0, v177
	v_cvt_pk_fp8_f32 v246, v0, v177
	v_add_f32_e32 v219, v179, v219
	v_add_f32_e32 v219, v254, v219
	v_cvt_pk_fp8_f32 v246, v179, v254 op_sel:[0,0,1]
	s_waitcnt lgkmcnt(2)
	v_mfma_scale_f32_32x32x64_f8f6f4 v[114:129], v[114:121], v[146:153], v[230:245], v194, v193 op_sel_hi:[0,0,0]
	v_exp_f32_e32 v0, v86
	v_exp_f32_e32 v177, v87
	v_exp_f32_e32 v179, v88
	v_exp_f32_e32 v254, v89
	v_add_f32_e32 v219, v0, v219
	v_add_f32_e32 v219, v177, v219
	v_cvt_pk_fp8_f32 v247, v0, v177
	v_add_f32_e32 v219, v179, v219
	v_add_f32_e32 v219, v254, v219
	v_cvt_pk_fp8_f32 v247, v179, v254 op_sel:[0,0,1]
	ds_read_b128 v[82:85], v213 offset:51200
	ds_read_b128 v[86:89], v214 offset:51200
	s_waitcnt lgkmcnt(2)
	v_mfma_scale_f32_32x32x64_f8f6f4 v[98:113], v[222:229], v[146:153], v[230:245], v194, v193 op_sel_hi:[0,0,0]
	ds_read_b128 v[222:225], v213 offset:55296
	ds_read_b128 v[226:229], v214 offset:55296
	v_exp_f32_e32 v0, v90
	v_exp_f32_e32 v177, v91
	v_exp_f32_e32 v179, v92
	v_exp_f32_e32 v254, v93
	v_add_f32_e32 v219, v0, v219
	v_add_f32_e32 v219, v177, v219
	v_cvt_pk_fp8_f32 v248, v0, v177
	v_add_f32_e32 v219, v179, v219
	v_add_f32_e32 v219, v254, v219
	v_cvt_pk_fp8_f32 v248, v179, v254 op_sel:[0,0,1]
	v_exp_f32_e32 v0, v94
	v_exp_f32_e32 v177, v95
	v_exp_f32_e32 v179, v96
	v_exp_f32_e32 v254, v97
	v_add_f32_e32 v219, v0, v219
	v_add_f32_e32 v219, v177, v219
	v_cvt_pk_fp8_f32 v249, v0, v177
	v_add_f32_e32 v219, v179, v219
	v_add_f32_e32 v219, v254, v219
	v_cvt_pk_fp8_f32 v249, v179, v254 op_sel:[0,0,1]
	ds_read_b128 v[90:93], v185 offset:59392
	ds_read_b128 v[94:97], v186 offset:59392
	s_waitcnt lgkmcnt(4)
	v_mfma_scale_f32_32x32x64_f8f6f4 v[114:129], v[82:89], v[138:145], v[114:129], v194, v193 op_sel_hi:[0,0,0]
	v_exp_f32_e32 v0, v66
	v_exp_f32_e32 v177, v67
	v_exp_f32_e32 v179, v68
	v_exp_f32_e32 v254, v69
	v_add_f32_e32 v219, v0, v219
	v_add_f32_e32 v219, v177, v219
	v_cvt_pk_fp8_f32 v250, v0, v177
	v_add_f32_e32 v219, v179, v219
	v_add_f32_e32 v219, v254, v219
	v_cvt_pk_fp8_f32 v250, v179, v254 op_sel:[0,0,1]
	s_waitcnt lgkmcnt(2)
	v_mfma_scale_f32_32x32x64_f8f6f4 v[98:113], v[222:229], v[138:145], v[98:113], v194, v193 op_sel_hi:[0,0,0]
	ds_read_b128 v[222:225], v185 offset:61440
	ds_read_b128 v[226:229], v186 offset:61440
	v_exp_f32_e32 v0, v70
	v_exp_f32_e32 v177, v71
	v_exp_f32_e32 v179, v72
	v_exp_f32_e32 v254, v73
	v_add_f32_e32 v219, v0, v219
	v_add_f32_e32 v219, v177, v219
	v_cvt_pk_fp8_f32 v251, v0, v177
	v_add_f32_e32 v219, v179, v219
	v_add_f32_e32 v219, v254, v219
	v_cvt_pk_fp8_f32 v251, v179, v254 op_sel:[0,0,1]
	v_exp_f32_e32 v0, v74
	v_exp_f32_e32 v177, v75
	v_exp_f32_e32 v179, v76
	v_exp_f32_e32 v254, v77
	v_add_f32_e32 v219, v0, v219
	v_add_f32_e32 v219, v177, v219
	v_cvt_pk_fp8_f32 v252, v0, v177
	v_add_f32_e32 v219, v179, v219
	v_add_f32_e32 v219, v254, v219
	v_cvt_pk_fp8_f32 v252, v179, v254 op_sel:[0,0,1]
	s_waitcnt lgkmcnt(2)
	v_mfma_scale_f32_32x32x64_f8f6f4 v[114:129], v[90:97], v[130:137], v[114:129], v194, v193 op_sel_hi:[0,0,0]
	v_exp_f32_e32 v0, v78
	v_exp_f32_e32 v177, v79
	v_exp_f32_e32 v179, v80
	v_exp_f32_e32 v254, v81
	v_add_f32_e32 v219, v0, v219
	v_add_f32_e32 v219, v177, v219
	v_cvt_pk_fp8_f32 v253, v0, v177
	v_add_f32_e32 v219, v179, v219
	v_add_f32_e32 v219, v254, v219
	v_cvt_pk_fp8_f32 v253, v179, v254 op_sel:[0,0,1]
	ds_read_b128 v[90:93], v185 offset:8192
	ds_read_b128 v[94:97], v186 offset:8192
	ds_read_b128 v[82:85], v185 offset:10240
	ds_read_b128 v[86:89], v186 offset:10240
	ds_read_b128 v[74:77], v185 offset:12288
	ds_read_b128 v[78:81], v186 offset:12288
	ds_read_b128 v[66:69], v185 offset:14336
	ds_read_b128 v[70:73], v186 offset:14336
	s_waitcnt lgkmcnt(8)
	v_mfma_scale_f32_32x32x64_f8f6f4 v[98:113], v[222:229], v[130:137], v[98:113], v194, v193 op_sel_hi:[0,0,0]
	v_mov_b32_e32 v0, v219
	s_nop 1
	v_permlane32_swap_b32_e32 v219, v0
	v_add_f32_e32 v219, v219, v0
	v_fma_f32 v209, v209, v218, v219
	v_max_f32_e32 v177, v114, v115
	v_max3_f32 v177, v177, v116, v117
	v_max3_f32 v177, v177, v118, v119
	v_max3_f32 v177, v177, v120, v121
	v_max3_f32 v177, v177, v122, v123
	v_max3_f32 v177, v177, v124, v125
	v_max3_f32 v177, v177, v126, v127
	v_max3_f32 v177, v177, v128, v129
	s_waitcnt lgkmcnt(6)
	v_mfma_scale_f32_32x32x64_f8f6f4 v[50:65], v[246:253], v[90:97], v[50:65], v194, v194 op_sel_hi:[0,0,0]
	s_waitcnt vmcnt(0)
	ds_write_b128 v210, v[158:161]
	ds_write_b128 v211, v[162:165] offset:16384
	s_waitcnt lgkmcnt(6)
	v_mfma_scale_f32_32x32x64_f8f6f4 v[34:49], v[246:253], v[82:89], v[34:49], v194, v194 op_sel_hi:[0,0,0]
	s_waitcnt lgkmcnt(0)
	s_barrier
	s_waitcnt lgkmcnt(2)
	v_mfma_scale_f32_32x32x64_f8f6f4 v[18:33], v[246:253], v[74:81], v[18:33], v194, v194 op_sel_hi:[0,0,0]
	global_load_dwordx4 v[158:161], v176, s[18:19]
	global_load_dwordx4 v[162:165], v178, s[16:17]
	v_add_u32_e32 v176, 0x2000, v176
	v_add_u32_e32 v178, 0x20000, v178
	s_waitcnt lgkmcnt(0)
	v_mfma_scale_f32_32x32x64_f8f6f4 v[2:17], v[246:253], v[66:73], v[2:17], v194, v194 op_sel_hi:[0,0,0]
	v_max_f32_e32 v0, v98, v99
	v_max3_f32 v0, v0, v100, v101
	v_max3_f32 v0, v0, v102, v103
	v_max3_f32 v0, v0, v104, v105
	v_max3_f32 v0, v0, v106, v107
	v_max3_f32 v0, v0, v108, v109
	v_max3_f32 v0, v0, v110, v111
	v_max3_f32 v0, v0, v112, v113
	v_max_f32_e32 v177, v177, v0
	v_mov_b32_e32 v0, v177
	v_mov_b32_e32 v221, 1.0
	s_nop 0
	v_permlane32_swap_b32_e32 v177, v0
	v_max_f32_e32 v177, v177, v0
	v_cmp_ge_f32_e32 vcc, s90, v177
	s_cmp_eq_u64 vcc, exec
	s_cbranch_scc0 .Lmla_s4_newmax
; __device__ __forceinline__ void finishSM9(f32x16& p0, f32x16& p1, float alpha, float& l_reg, v8i32& p8) {
; #pragma unroll
;   for (int r = 0; r < 16; ++r) { p0[r] = __builtin_amdgcn_exp2f(p0[r]); p1[r] = __builtin_amdgcn_exp2f(p1[r]); }
;   float ps = 0;
; #pragma unroll
;   for (int r = 0; r < 16; ++r) ps += p0[r];
; #pragma unroll
;   for (int r = 0; r < 16; ++r) ps += p1[r];
;   { auto rr = __builtin_amdgcn_permlane32_swap(__float_as_uint(ps), __float_as_uint(ps), false, false);
;     ps = __uint_as_float(rr[0]) + __uint_as_float(rr[1]); }
;   l_reg = l_reg * alpha + ps;
; #pragma unroll
;   for (int g = 0; g < 4; ++g) {
;     int w = __builtin_amdgcn_cvt_pk_fp8_f32(p0[4 * g], p0[4 * g + 1], 0, false); p8[g] = __builtin_amdgcn_cvt_pk_fp8_f32(p0[4 * g + 2], p0[4 * g + 3], w, true);
;     int u = __builtin_amdgcn_cvt_pk_fp8_f32(p1[4 * g], p1[4 * g + 1], 0, false); p8[4 + g] = __builtin_amdgcn_cvt_pk_fp8_f32(p1[4 * g + 2], p1[4 * g + 3], u, true); }
; }
; __device__ __forceinline__ void pv8(f32x16* o, const char* Vt, const v8i32 p8, int r32, int hi) {
;   const int sw = (r32 >> 2) & 3, a0 = r32 * 64 + (((hi * 2) ^ sw) << 4), a1 = r32 * 64 + (((hi * 2 + 1) ^ sw) << 4);
; #pragma unroll
;   for (int d0 = 0; d0 < 4; ++d0) {
;     const v8i32 vf = cat8(*reinterpret_cast<const v4i32*>(Vt + d0 * 2048 + a0), *reinterpret_cast<const v4i32*>(Vt + d0 * 2048 + a1));
;     o[d0] = __builtin_amdgcn_mfma_scale_f32_32x32x64_f8f6f4(p8, vf, o[d0], 0, 0, 0, 127, 0, 127); }
; }
; __device__ __forceinline__ void qkt9(f32x16& p0, f32x16& p1, const char* Kn, const char* Kr, const v8i32* qf, const float init, int r32, int hi) {
; #pragma unroll
;   for (int r = 0; r < 16; ++r) { p0[r] = init; p1[r] = init; }
; #pragma unroll
;   for (int s = 0; s < 2; ++s) { const int c0 = s * 4 + hi * 2;
;     const v8i32 a0 = cat8(*reinterpret_cast<const v4i32*>(Kn + KN8SW(r32, c0)), *reinterpret_cast<const v4i32*>(Kn + KN8SW(r32, c0 + 1)));
;     const v8i32 a1 = cat8(*reinterpret_cast<const v4i32*>(Kn + 4096 + KN8SW(r32, c0)), *reinterpret_cast<const v4i32*>(Kn + 4096 + KN8SW(r32, c0 + 1)));
;     p0 = __builtin_amdgcn_mfma_scale_f32_32x32x64_f8f6f4(a0, qf[s], p0, 0, 0, 0, 127, 0, 124);
;     p1 = __builtin_amdgcn_mfma_scale_f32_32x32x64_f8f6f4(a1, qf[s], p1, 0, 0, 0, 127, 0, 124); }
;   { const int c0 = hi * 2;
.Lmla_s4_cont:
	ds_read_b128 v[82:85], v215 offset:16384
	ds_read_b128 v[86:89], v216 offset:16384
	ds_read_b128 v[222:225], v215 offset:20480
	ds_read_b128 v[226:229], v216 offset:20480
	v_exp_f32_e32 v0, v114
	v_exp_f32_e32 v177, v115
	v_exp_f32_e32 v179, v116
	v_exp_f32_e32 v254, v117
	v_add_f32_e32 v219, v0, v177
	v_cvt_pk_fp8_f32 v246, v0, v177
	v_add_f32_e32 v219, v179, v219
	v_add_f32_e32 v219, v254, v219
	v_cvt_pk_fp8_f32 v246, v179, v254 op_sel:[0,0,1]
	s_waitcnt lgkmcnt(2)
	v_mfma_scale_f32_32x32x64_f8f6f4 v[82:97], v[82:89], v[146:153], v[230:245], v194, v193 op_sel_hi:[0,0,0]
	v_exp_f32_e32 v0, v118
	v_exp_f32_e32 v177, v119
	v_exp_f32_e32 v179, v120
	v_exp_f32_e32 v254, v121
	v_add_f32_e32 v219, v0, v219
	v_add_f32_e32 v219, v177, v219
	v_cvt_pk_fp8_f32 v247, v0, v177
	v_add_f32_e32 v219, v179, v219
	v_add_f32_e32 v219, v254, v219
	v_cvt_pk_fp8_f32 v247, v179, v254 op_sel:[0,0,1]
	ds_read_b128 v[114:117], v213 offset:16384
	ds_read_b128 v[118:121], v214 offset:16384
	s_waitcnt lgkmcnt(2)
	v_mfma_scale_f32_32x32x64_f8f6f4 v[66:81], v[222:229], v[146:153], v[230:245], v194, v193 op_sel_hi:[0,0,0]
	ds_read_b128 v[222:225], v213 offset:20480
	ds_read_b128 v[226:229], v214 offset:20480
	v_exp_f32_e32 v0, v122
	v_exp_f32_e32 v177, v123
	v_exp_f32_e32 v179, v124
	v_exp_f32_e32 v254, v125
	v_add_f32_e32 v219, v0, v219
	v_add_f32_e32 v219, v177, v219
	v_cvt_pk_fp8_f32 v248, v0, v177
	v_add_f32_e32 v219, v179, v219
	v_add_f32_e32 v219, v254, v219
	v_cvt_pk_fp8_f32 v248, v179, v254 op_sel:[0,0,1]
	v_exp_f32_e32 v0, v126
	v_exp_f32_e32 v177, v127
	v_exp_f32_e32 v179, v128
	v_exp_f32_e32 v254, v129
	v_add_f32_e32 v219, v0, v219
	v_add_f32_e32 v219, v177, v219
	v_cvt_pk_fp8_f32 v249, v0, v177
	v_add_f32_e32 v219, v179, v219
	v_add_f32_e32 v219, v254, v219
	v_cvt_pk_fp8_f32 v249, v179, v254 op_sel:[0,0,1]
	ds_read_b128 v[122:125], v185 offset:32768
	ds_read_b128 v[126:129], v186 offset:32768
	s_waitcnt lgkmcnt(4)
	v_mfma_scale_f32_32x32x64_f8f6f4 v[82:97], v[114:121], v[138:145], v[82:97], v194, v193 op_sel_hi:[0,0,0]
	v_exp_f32_e32 v0, v98
	v_exp_f32_e32 v177, v99
	v_exp_f32_e32 v179, v100
	v_exp_f32_e32 v254, v101
	v_add_f32_e32 v219, v0, v219
	v_add_f32_e32 v219, v177, v219
	v_cvt_pk_fp8_f32 v250, v0, v177
	v_add_f32_e32 v219, v179, v219
	v_add_f32_e32 v219, v254, v219
	v_cvt_pk_fp8_f32 v250, v179, v254 op_sel:[0,0,1]
	s_waitcnt lgkmcnt(2)
	v_mfma_scale_f32_32x32x64_f8f6f4 v[66:81], v[222:229], v[138:145], v[66:81], v194, v193 op_sel_hi:[0,0,0]
	ds_read_b128 v[222:225], v185 offset:34816
	ds_read_b128 v[226:229], v186 offset:34816
	v_exp_f32_e32 v0, v102
	v_exp_f32_e32 v177, v103
	v_exp_f32_e32 v179, v104
	v_exp_f32_e32 v254, v105
	v_add_f32_e32 v219, v0, v219
	v_add_f32_e32 v219, v177, v219
	v_cvt_pk_fp8_f32 v251, v0, v177
	v_add_f32_e32 v219, v179, v219
	v_add_f32_e32 v219, v254, v219
	v_cvt_pk_fp8_f32 v251, v179, v254 op_sel:[0,0,1]
	v_exp_f32_e32 v0, v106
	v_exp_f32_e32 v177, v107
	v_exp_f32_e32 v179, v108
	v_exp_f32_e32 v254, v109
	v_add_f32_e32 v219, v0, v219
	v_add_f32_e32 v219, v177, v219
	v_cvt_pk_fp8_f32 v252, v0, v177
	v_add_f32_e32 v219, v179, v219
	v_add_f32_e32 v219, v254, v219
	v_cvt_pk_fp8_f32 v252, v179, v254 op_sel:[0,0,1]
	s_waitcnt lgkmcnt(2)
	v_mfma_scale_f32_32x32x64_f8f6f4 v[82:97], v[122:129], v[130:137], v[82:97], v194, v193 op_sel_hi:[0,0,0]
	v_exp_f32_e32 v0, v110
	v_exp_f32_e32 v177, v111
	v_exp_f32_e32 v179, v112
	v_exp_f32_e32 v254, v113
	v_add_f32_e32 v219, v0, v219
	v_add_f32_e32 v219, v177, v219
	v_cvt_pk_fp8_f32 v253, v0, v177
	v_add_f32_e32 v219, v179, v219
	v_add_f32_e32 v219, v254, v219
	v_cvt_pk_fp8_f32 v253, v179, v254 op_sel:[0,0,1]
	ds_read_b128 v[122:125], v185 offset:43008
	ds_read_b128 v[126:129], v186 offset:43008
	ds_read_b128 v[114:117], v185 offset:45056
	ds_read_b128 v[118:121], v186 offset:45056
	ds_read_b128 v[106:109], v185 offset:47104
	ds_read_b128 v[110:113], v186 offset:47104
	ds_read_b128 v[98:101], v185 offset:49152
	ds_read_b128 v[102:105], v186 offset:49152
	s_waitcnt lgkmcnt(8)
	v_mfma_scale_f32_32x32x64_f8f6f4 v[66:81], v[222:229], v[130:137], v[66:81], v194, v193 op_sel_hi:[0,0,0]
	v_mov_b32_e32 v0, v219
	s_nop 1
	v_permlane32_swap_b32_e32 v219, v0
	v_add_f32_e32 v219, v219, v0
	v_fma_f32 v209, v209, v221, v219
	v_max_f32_e32 v177, v82, v83
	v_max3_f32 v177, v177, v84, v85
	v_max3_f32 v177, v177, v86, v87
	v_max3_f32 v177, v177, v88, v89
	v_max3_f32 v177, v177, v90, v91
	v_max3_f32 v177, v177, v92, v93
	v_max3_f32 v177, v177, v94, v95
	v_max3_f32 v177, v177, v96, v97
	s_waitcnt lgkmcnt(6)
	v_mfma_scale_f32_32x32x64_f8f6f4 v[50:65], v[246:253], v[122:129], v[50:65], v194, v194 op_sel_hi:[0,0,0]
	s_waitcnt vmcnt(0)
	ds_write_b128 v210, v[158:161] offset:8192
	ds_write_b128 v211, v[162:165] offset:24576
	s_waitcnt lgkmcnt(6)
	v_mfma_scale_f32_32x32x64_f8f6f4 v[34:49], v[246:253], v[114:121], v[34:49], v194, v194 op_sel_hi:[0,0,0]
	s_waitcnt lgkmcnt(0)
	s_barrier
	s_waitcnt lgkmcnt(2)
	v_mfma_scale_f32_32x32x64_f8f6f4 v[18:33], v[246:253], v[106:113], v[18:33], v194, v194 op_sel_hi:[0,0,0]
	global_load_dwordx4 v[158:161], v176, s[18:19]
	global_load_dwordx4 v[162:165], v178, s[16:17]
	v_add_u32_e32 v176, 0x2000, v176
	v_add_u32_e32 v178, 0x20000, v178
	s_waitcnt lgkmcnt(0)
	v_mfma_scale_f32_32x32x64_f8f6f4 v[2:17], v[246:253], v[98:105], v[2:17], v194, v194 op_sel_hi:[0,0,0]
	v_max_f32_e32 v0, v66, v67
	v_max3_f32 v0, v0, v68, v69
	v_max3_f32 v0, v0, v70, v71
	v_max3_f32 v0, v0, v72, v73
	v_max3_f32 v0, v0, v74, v75
	v_max3_f32 v0, v0, v76, v77
	v_max3_f32 v0, v0, v78, v79
	v_max3_f32 v0, v0, v80, v81
	v_max_f32_e32 v177, v177, v0
	v_mov_b32_e32 v0, v177
	v_mov_b32_e32 v218, 1.0
	s_nop 0
	v_permlane32_swap_b32_e32 v177, v0
	v_max_f32_e32 v177, v177, v0
	v_cmp_ge_f32_e32 vcc, s90, v177
	s_cmp_eq_u64 vcc, exec
	s_cbranch_scc0 .Lmla_s5_newmax
; __device__ __forceinline__ void finishSM9(f32x16& p0, f32x16& p1, float alpha, float& l_reg, v8i32& p8) {
; #pragma unroll
;   for (int r = 0; r < 16; ++r) { p0[r] = __builtin_amdgcn_exp2f(p0[r]); p1[r] = __builtin_amdgcn_exp2f(p1[r]); }
;   float ps = 0;
; #pragma unroll
;   for (int r = 0; r < 16; ++r) ps += p0[r];
; #pragma unroll
;   for (int r = 0; r < 16; ++r) ps += p1[r];
;   { auto rr = __builtin_amdgcn_permlane32_swap(__float_as_uint(ps), __float_as_uint(ps), false, false);
;     ps = __uint_as_float(rr[0]) + __uint_as_float(rr[1]); }
;   l_reg = l_reg * alpha + ps;
; #pragma unroll
;   for (int g = 0; g < 4; ++g) {
;     int w = __builtin_amdgcn_cvt_pk_fp8_f32(p0[4 * g], p0[4 * g + 1], 0, false); p8[g] = __builtin_amdgcn_cvt_pk_fp8_f32(p0[4 * g + 2], p0[4 * g + 3], w, true);
;     int u = __builtin_amdgcn_cvt_pk_fp8_f32(p1[4 * g], p1[4 * g + 1], 0, false); p8[4 + g] = __builtin_amdgcn_cvt_pk_fp8_f32(p1[4 * g + 2], p1[4 * g + 3], u, true); }
; }
; __device__ __forceinline__ void pv8(f32x16* o, const char* Vt, const v8i32 p8, int r32, int hi) {
;   const int sw = (r32 >> 2) & 3, a0 = r32 * 64 + (((hi * 2) ^ sw) << 4), a1 = r32 * 64 + (((hi * 2 + 1) ^ sw) << 4);
; #pragma unroll
;   for (int d0 = 0; d0 < 4; ++d0) {
;     const v8i32 vf = cat8(*reinterpret_cast<const v4i32*>(Vt + d0 * 2048 + a0), *reinterpret_cast<const v4i32*>(Vt + d0 * 2048 + a1));
;     o[d0] = __builtin_amdgcn_mfma_scale_f32_32x32x64_f8f6f4(p8, vf, o[d0], 0, 0, 0, 127, 0, 127); }
; }
; __device__ __forceinline__ void qkt9(f32x16& p0, f32x16& p1, const char* Kn, const char* Kr, const v8i32* qf, const float init, int r32, int hi) {
; #pragma unroll
;   for (int r = 0; r < 16; ++r) { p0[r] = init; p1[r] = init; }
; #pragma unroll
;   for (int s = 0; s < 2; ++s) { const int c0 = s * 4 + hi * 2;
;     const v8i32 a0 = cat8(*reinterpret_cast<const v4i32*>(Kn + KN8SW(r32, c0)), *reinterpret_cast<const v4i32*>(Kn + KN8SW(r32, c0 + 1)));
;     const v8i32 a1 = cat8(*reinterpret_cast<const v4i32*>(Kn + 4096 + KN8SW(r32, c0)), *reinterpret_cast<const v4i32*>(Kn + 4096 + KN8SW(r32, c0 + 1)));
;     p0 = __builtin_amdgcn_mfma_scale_f32_32x32x64_f8f6f4(a0, qf[s], p0, 0, 0, 0, 127, 0, 124);
;     p1 = __builtin_amdgcn_mfma_scale_f32_32x32x64_f8f6f4(a1, qf[s], p1, 0, 0, 0, 127, 0, 124); }
;   { const int c0 = hi * 2;
.Lmla_s5_cont:
	s_add_i32 s30, s30, 1
	s_cmpk_lt_u32 s30, 42
	s_cbranch_scc1 .Lmla_stag_loop
	ds_read_b128 v[114:117], v215 offset:24576
	ds_read_b128 v[118:121], v216 offset:24576
	ds_read_b128 v[222:225], v215 offset:28672
	ds_read_b128 v[226:229], v216 offset:28672
	v_exp_f32_e32 v0, v82
	v_exp_f32_e32 v177, v83
	v_exp_f32_e32 v179, v84
	v_exp_f32_e32 v254, v85
	v_add_f32_e32 v219, v0, v177
	v_cvt_pk_fp8_f32 v246, v0, v177
	v_add_f32_e32 v219, v179, v219
	v_add_f32_e32 v219, v254, v219
	v_cvt_pk_fp8_f32 v246, v179, v254 op_sel:[0,0,1]
	s_waitcnt lgkmcnt(2)
	v_mfma_scale_f32_32x32x64_f8f6f4 v[114:129], v[114:121], v[146:153], v[230:245], v194, v193 op_sel_hi:[0,0,0]
	v_exp_f32_e32 v0, v86
	v_exp_f32_e32 v177, v87
	v_exp_f32_e32 v179, v88
	v_exp_f32_e32 v254, v89
	v_add_f32_e32 v219, v0, v219
	v_add_f32_e32 v219, v177, v219
	v_cvt_pk_fp8_f32 v247, v0, v177
	v_add_f32_e32 v219, v179, v219
	v_add_f32_e32 v219, v254, v219
	v_cvt_pk_fp8_f32 v247, v179, v254 op_sel:[0,0,1]
	ds_read_b128 v[82:85], v213 offset:24576
	ds_read_b128 v[86:89], v214 offset:24576
	s_waitcnt lgkmcnt(2)
	v_mfma_scale_f32_32x32x64_f8f6f4 v[98:113], v[222:229], v[146:153], v[230:245], v194, v193 op_sel_hi:[0,0,0]
	ds_read_b128 v[222:225], v213 offset:28672
	ds_read_b128 v[226:229], v214 offset:28672
	v_exp_f32_e32 v0, v90
	v_exp_f32_e32 v177, v91
	v_exp_f32_e32 v179, v92
	v_exp_f32_e32 v254, v93
	v_add_f32_e32 v219, v0, v219
	v_add_f32_e32 v219, v177, v219
	v_cvt_pk_fp8_f32 v248, v0, v177
	v_add_f32_e32 v219, v179, v219
	v_add_f32_e32 v219, v254, v219
	v_cvt_pk_fp8_f32 v248, v179, v254 op_sel:[0,0,1]
	v_exp_f32_e32 v0, v94
	v_exp_f32_e32 v177, v95
	v_exp_f32_e32 v179, v96
	v_exp_f32_e32 v254, v97
	v_add_f32_e32 v219, v0, v219
	v_add_f32_e32 v219, v177, v219
	v_cvt_pk_fp8_f32 v249, v0, v177
	v_add_f32_e32 v219, v179, v219
	v_add_f32_e32 v219, v254, v219
	v_cvt_pk_fp8_f32 v249, v179, v254 op_sel:[0,0,1]
	ds_read_b128 v[90:93], v185 offset:36864
	ds_read_b128 v[94:97], v186 offset:36864
	s_waitcnt lgkmcnt(4)
	v_mfma_scale_f32_32x32x64_f8f6f4 v[114:129], v[82:89], v[138:145], v[114:129], v194, v193 op_sel_hi:[0,0,0]
	v_exp_f32_e32 v0, v66
	v_exp_f32_e32 v177, v67
	v_exp_f32_e32 v179, v68
	v_exp_f32_e32 v254, v69
	v_add_f32_e32 v219, v0, v219
	v_add_f32_e32 v219, v177, v219
	v_cvt_pk_fp8_f32 v250, v0, v177
	v_add_f32_e32 v219, v179, v219
	v_add_f32_e32 v219, v254, v219
	v_cvt_pk_fp8_f32 v250, v179, v254 op_sel:[0,0,1]
	s_waitcnt lgkmcnt(2)
	v_mfma_scale_f32_32x32x64_f8f6f4 v[98:113], v[222:229], v[138:145], v[98:113], v194, v193 op_sel_hi:[0,0,0]
	ds_read_b128 v[222:225], v185 offset:38912
	ds_read_b128 v[226:229], v186 offset:38912
	v_exp_f32_e32 v0, v70
	v_exp_f32_e32 v177, v71
	v_exp_f32_e32 v179, v72
	v_exp_f32_e32 v254, v73
	v_add_f32_e32 v219, v0, v219
	v_add_f32_e32 v219, v177, v219
	v_cvt_pk_fp8_f32 v251, v0, v177
	v_add_f32_e32 v219, v179, v219
	v_add_f32_e32 v219, v254, v219
	v_cvt_pk_fp8_f32 v251, v179, v254 op_sel:[0,0,1]
	v_exp_f32_e32 v0, v74
	v_exp_f32_e32 v177, v75
	v_exp_f32_e32 v179, v76
	v_exp_f32_e32 v254, v77
	v_add_f32_e32 v219, v0, v219
	v_add_f32_e32 v219, v177, v219
	v_cvt_pk_fp8_f32 v252, v0, v177
	v_add_f32_e32 v219, v179, v219
	v_add_f32_e32 v219, v254, v219
	v_cvt_pk_fp8_f32 v252, v179, v254 op_sel:[0,0,1]
	s_waitcnt lgkmcnt(2)
	v_mfma_scale_f32_32x32x64_f8f6f4 v[114:129], v[90:97], v[130:137], v[114:129], v194, v193 op_sel_hi:[0,0,0]
	v_exp_f32_e32 v0, v78
	v_exp_f32_e32 v177, v79
	v_exp_f32_e32 v179, v80
	v_exp_f32_e32 v254, v81
	v_add_f32_e32 v219, v0, v219
	v_add_f32_e32 v219, v177, v219
	v_cvt_pk_fp8_f32 v253, v0, v177
	v_add_f32_e32 v219, v179, v219
	v_add_f32_e32 v219, v254, v219
	v_cvt_pk_fp8_f32 v253, v179, v254 op_sel:[0,0,1]
	ds_read_b128 v[90:93], v185 offset:0
	ds_read_b128 v[94:97], v186 offset:0
	ds_read_b128 v[82:85], v185 offset:2048
	ds_read_b128 v[86:89], v186 offset:2048
	ds_read_b128 v[74:77], v185 offset:4096
	ds_read_b128 v[78:81], v186 offset:4096
	ds_read_b128 v[66:69], v185 offset:6144
	ds_read_b128 v[70:73], v186 offset:6144
	s_waitcnt lgkmcnt(8)
	v_mfma_scale_f32_32x32x64_f8f6f4 v[98:113], v[222:229], v[130:137], v[98:113], v194, v193 op_sel_hi:[0,0,0]
	v_mov_b32_e32 v0, v219
	s_nop 1
	v_permlane32_swap_b32_e32 v219, v0
	v_add_f32_e32 v219, v219, v0
	v_fma_f32 v209, v209, v218, v219
	v_max_f32_e32 v177, v114, v115
	v_max3_f32 v177, v177, v116, v117
	v_max3_f32 v177, v177, v118, v119
	v_max3_f32 v177, v177, v120, v121
	v_max3_f32 v177, v177, v122, v123
	v_max3_f32 v177, v177, v124, v125
	v_max3_f32 v177, v177, v126, v127
	v_max3_f32 v177, v177, v128, v129
	s_waitcnt lgkmcnt(6)
	v_mfma_scale_f32_32x32x64_f8f6f4 v[50:65], v[246:253], v[90:97], v[50:65], v194, v194 op_sel_hi:[0,0,0]
	s_waitcnt vmcnt(0)
	ds_write_b128 v210, v[158:161] offset:43008
	ds_write_b128 v211, v[162:165] offset:51200
	s_waitcnt lgkmcnt(6)
	v_mfma_scale_f32_32x32x64_f8f6f4 v[34:49], v[246:253], v[82:89], v[34:49], v194, v194 op_sel_hi:[0,0,0]
	s_waitcnt lgkmcnt(0)
	s_barrier
	s_waitcnt lgkmcnt(2)
	v_mfma_scale_f32_32x32x64_f8f6f4 v[18:33], v[246:253], v[74:81], v[18:33], v194, v194 op_sel_hi:[0,0,0]
	global_load_dwordx4 v[158:161], v176, s[18:19]
	global_load_dwordx4 v[162:165], v178, s[16:17]
	v_add_u32_e32 v176, 0x2000, v176
	v_add_u32_e32 v178, 0x20000, v178
	s_waitcnt lgkmcnt(0)
	v_mfma_scale_f32_32x32x64_f8f6f4 v[2:17], v[246:253], v[66:73], v[2:17], v194, v194 op_sel_hi:[0,0,0]
	v_max_f32_e32 v0, v98, v99
	v_max3_f32 v0, v0, v100, v101
	v_max3_f32 v0, v0, v102, v103
	v_max3_f32 v0, v0, v104, v105
	v_max3_f32 v0, v0, v106, v107
	v_max3_f32 v0, v0, v108, v109
	v_max3_f32 v0, v0, v110, v111
	v_max3_f32 v0, v0, v112, v113
	v_max_f32_e32 v177, v177, v0
	v_mov_b32_e32 v0, v177
	v_mov_b32_e32 v221, 1.0
	s_nop 0
	v_permlane32_swap_b32_e32 v177, v0
	v_max_f32_e32 v177, v177, v0
	v_cmp_ge_f32_e32 vcc, s90, v177
	s_cmp_eq_u64 vcc, exec
	s_cbranch_scc0 .Lmla_q0_newmax
